# p5epi
# speedup vs baseline: 1.0166x; 1.0062x over previous
; template <int EPI>
; __device__ __forceinline__ void gemm_phase(const u16* __restrict__ A, const u16* __restrict__ Bt, const int K,
;                                            const int nN, char* shm, const EpiArgs& ea) {
;     ...
;               float mu = 0.f, rstd = 1.f;
;               if (EPI != EPI_FFN1) row_stats(ea.st_in, row, mu, rstd);
;               float rs = 0.f, rq = 0.f;
; #pragma unroll
;               for (int bj = 0; bj < 2; ++bj) {
;                 uint2 pk[2];
; #pragma unroll
;                 for (int n = 0; n < 2; ++n) {
;                   const int col = cb + bj * 128 + n * 16;
;                   f32x4 c = acc[ai][bj][m][n];
;                   float h[4];
;                   if (EPI == EPI_FFN1) {
;                     float4 rv = *(const float4*)(ea.res + (size_t)row * DM + col);
;                     h[0] = rv.x; h[1] = rv.y; h[2] = rv.z; h[3] = rv.w;
;                   } else {
;                     uint2 yv = *(const uint2*)((const char*)ea.yb + tl_off(row, col, DM >> 6));
;                     float4 gv = *(const float4*)(ea.lng + col);
;                     float4 bv = *(const float4*)(ea.lnb + col);
;                     h[0] = (bf_lo(yv.x) - mu) * rstd * gv.x + bv.x; h[1] = (bf_hi(yv.x) - mu) * rstd * gv.y + bv.y;
;                     h[2] = (bf_lo(yv.y) - mu) * rstd * gv.z + bv.z; h[3] = (bf_hi(yv.y) - mu) * rstd * gv.w + bv.w;
;                   }
;                   float y[4];
;                   if (EPI == EPI_OUT) {
;                     float4 bo = *(const float4*)(ea.bias + col);
;                     y[0] = ALPHA * h[0] + c[0] + bo.x; y[1] = ALPHA * h[1] + c[1] + bo.y;
;                     y[2] = ALPHA * h[2] + c[2] + bo.z; y[3] = ALPHA * h[3] + c[3] + bo.w;
;                   } else {
; #pragma unroll
;                     for (int j = 0; j < 4; ++j) y[j] = ALPHA * h[j] + 0.5f * c[j];
;                   }
;                   if (EPI == EPI_FFN2) {
;                     *(float4*)(ea.outf + (size_t)row * DM + col) = make_float4(y[0], y[1], y[2], y[3]);
;                   } else {
;                     pk[n] = make_uint2(pack2(y[0], y[1]), pack2(y[2], y[3]));
;                     float q0 = bf_lo(pk[n].x), q1 = bf_hi(pk[n].x), q2 = bf_lo(pk[n].y), q3 = bf_hi(pk[n].y);
;                     rs += (q0 + q1) + (q2 + q3);
;                     rq += (q0 * q0 + q1 * q1) + (q2 * q2 + q3 * q3);
;                   }
.LBB0_497:
	s_lshr_b32 s98, s58, 7
	s_mul_i32 s98, s98, 0x84000
	s_lshr_b32 s99, s33, 6
	s_lshl_b32 s99, s99, 14
	s_add_i32 s98, s98, s99
	s_add_i32 s99, s33, s53
	v_add_u32_e32 v130, s58, v143
	v_add_u32_e32 v131, s99, v144
	v_lshlrev_b32_e32 v175, 3, v130
	v_lshlrev_b32_e32 v133, 2, v131
	global_load_dwordx2 v[156:157], v175, s[6:7]
	global_load_dwordx2 v[158:159], v175, s[6:7] offset:128
	global_load_dwordx2 v[160:161], v175, s[6:7] offset:256
	global_load_dwordx2 v[162:163], v175, s[6:7] offset:384
	global_load_dwordx4 v[176:179], v133, s[44:45]
	global_load_dwordx4 v[192:195], v133, s[46:47]
	global_load_dwordx4 v[208:211], v133, s[20:21]
	global_load_dwordx4 v[180:183], v133, s[44:45] offset:64
	global_load_dwordx4 v[196:199], v133, s[46:47] offset:64
	global_load_dwordx4 v[212:215], v133, s[20:21] offset:64
	global_load_dwordx4 v[184:187], v133, s[44:45] offset:512
	global_load_dwordx4 v[200:203], v133, s[46:47] offset:512
	global_load_dwordx4 v[216:219], v133, s[20:21] offset:512
	global_load_dwordx4 v[188:191], v133, s[44:45] offset:576
	global_load_dwordx4 v[204:207], v133, s[46:47] offset:576
	global_load_dwordx4 v[220:223], v133, s[20:21] offset:576
	v_and_b32_e32 v130, 15, v174
	v_lshlrev_b32_e32 v128, 6, v130
	v_and_b32_e32 v130, 64, v174
	v_lshl_or_b32 v128, v130, 4, v128
	v_and_b32_e32 v130, 0x80, v174
	v_lshl_or_b32 v128, v130, 7, v128
	v_and_b32_e32 v130, 0x100, v174
	v_lshl_or_b32 v128, v130, 5, v128
	v_add_u32_e32 v128, s98, v128
	v_and_b32_e32 v130, 48, v174
	v_lshrrev_b32_e32 v130, 1, v130
	v_or_b32_e32 v172, v128, v130
	v_and_b32_e32 v131, 8, v174
	v_lshlrev_b32_e32 v131, 2, v131
	v_sub_u32_e32 v173, v172, v131
	v_add_u32_e32 v173, 32, v173
	v_add_u32_e32 v172, v172, v131
	v_and_b32_e32 v130, 32, v174
	v_lshrrev_b32_e32 v130, 1, v130
	v_or_b32_e32 v128, v128, v130
	v_lshrrev_b32_e32 v130, 1, v174
	v_xor_b32_e32 v130, v130, v174
	v_and_b32_e32 v130, 8, v130
	v_lshl_or_b32 v128, v130, 2, v128
	global_load_dwordx2 v[224:225], v172, s[14:15]
	global_load_dwordx2 v[226:227], v173, s[14:15]
	v_add_u32_e32 v130, 0x8000, v172
	global_load_dwordx2 v[228:229], v130, s[14:15]
	v_add_u32_e32 v131, 0x8000, v173
	global_load_dwordx2 v[230:231], v131, s[14:15]
	v_add_u32_e32 v130, 0x800, v172
	global_load_dwordx2 v[232:233], v130, s[14:15]
	v_add_u32_e32 v131, 0x800, v173
	global_load_dwordx2 v[234:235], v131, s[14:15]
	v_add_u32_e32 v130, 0x8800, v172
	global_load_dwordx2 v[236:237], v130, s[14:15]
	v_add_u32_e32 v131, 0x8800, v173
	global_load_dwordx2 v[238:239], v131, s[14:15]
	v_add_u32_e32 v130, 0x1000, v172
	global_load_dwordx2 v[240:241], v130, s[14:15]
	v_add_u32_e32 v131, 0x1000, v173
	global_load_dwordx2 v[242:243], v131, s[14:15]
	v_add_u32_e32 v130, 0x9000, v172
	global_load_dwordx2 v[246:247], v130, s[14:15]
	v_add_u32_e32 v131, 0x9000, v173
	global_load_dwordx2 v[248:249], v131, s[14:15]
	v_add_u32_e32 v130, 0x1800, v172
	global_load_dwordx2 v[250:251], v130, s[14:15]
	v_add_u32_e32 v131, 0x1800, v173
	global_load_dwordx2 v[252:253], v131, s[14:15]
	v_add_u32_e32 v130, 0x9800, v172
	global_load_dwordx2 v[254:255], v130, s[14:15]
	v_add_u32_e32 v131, 0x9800, v173
	global_load_dwordx2 v[154:155], v131, s[14:15]
	s_waitcnt vmcnt(31)
	v_pk_mul_f32 v[156:157], v[156:157], s[24:25] op_sel_hi:[1,0]
	v_mov_b32_e32 v132, v128
	v_fma_f32 v164, -v156, v156, v157
	v_max_f32_e32 v164, 0, v164
	v_add_f32_e32 v164, 0x3727c5ac, v164
	v_rsq_f32_e32 v164, v164
	v_mov_b32_e32 v134, 0
	v_mov_b32_e32 v135, 0
	s_waitcnt vmcnt(16)
	s_waitcnt vmcnt(15)
	v_lshlrev_b32_e32 v168, 16, v224
	v_and_b32_e32 v169, 0xffff0000, v224
	v_lshlrev_b32_e32 v170, 16, v225
	v_and_b32_e32 v171, 0xffff0000, v225
	v_pk_add_f32 v[168:169], v[168:169], v[156:157] op_sel_hi:[1,0] neg_lo:[0,1] neg_hi:[0,1]
	v_pk_add_f32 v[170:171], v[170:171], v[156:157] op_sel_hi:[1,0] neg_lo:[0,1] neg_hi:[0,1]
	v_pk_mul_f32 v[168:169], v[168:169], v[164:165] op_sel_hi:[1,0]
	v_pk_mul_f32 v[170:171], v[170:171], v[164:165] op_sel_hi:[1,0]
	v_pk_fma_f32 v[168:169], v[176:177], v[168:169], v[192:193]
	v_pk_fma_f32 v[170:171], v[178:179], v[170:171], v[194:195]
	v_pk_fma_f32 v[124:125], v[168:169], s[26:27], v[124:125] op_sel_hi:[1,0,1]
	v_pk_fma_f32 v[126:127], v[170:171], s[26:27], v[126:127] op_sel_hi:[1,0,1]
	v_pk_add_f32 v[124:125], v[208:209], v[124:125]
	v_pk_add_f32 v[126:127], v[210:211], v[126:127]
	v_cvt_pk_bf16_f32 v136, v124, v125
	v_cvt_pk_bf16_f32 v137, v126, v127
	v_lshlrev_b32_e32 v168, 16, v136
	v_and_b32_e32 v169, 0xffff0000, v136
	v_lshlrev_b32_e32 v170, 16, v137
	v_and_b32_e32 v171, 0xffff0000, v137
	v_add_f32_e32 v134, v134, v168
	v_fmac_f32_e32 v135, v168, v168
	v_add_f32_e32 v134, v134, v169
	v_fmac_f32_e32 v135, v169, v169
	v_add_f32_e32 v134, v134, v170
	v_fmac_f32_e32 v135, v170, v170
	v_add_f32_e32 v134, v134, v171
	v_fmac_f32_e32 v135, v171, v171
	s_waitcnt vmcnt(14)
	v_lshlrev_b32_e32 v168, 16, v226
	v_and_b32_e32 v169, 0xffff0000, v226
	v_lshlrev_b32_e32 v170, 16, v227
	v_and_b32_e32 v171, 0xffff0000, v227
	v_pk_add_f32 v[168:169], v[168:169], v[156:157] op_sel_hi:[1,0] neg_lo:[0,1] neg_hi:[0,1]
	v_pk_add_f32 v[170:171], v[170:171], v[156:157] op_sel_hi:[1,0] neg_lo:[0,1] neg_hi:[0,1]
	v_pk_mul_f32 v[168:169], v[168:169], v[164:165] op_sel_hi:[1,0]
	v_pk_mul_f32 v[170:171], v[170:171], v[164:165] op_sel_hi:[1,0]
	v_pk_fma_f32 v[168:169], v[180:181], v[168:169], v[196:197]
	v_pk_fma_f32 v[170:171], v[182:183], v[170:171], v[198:199]
	v_pk_fma_f32 v[120:121], v[168:169], s[26:27], v[120:121] op_sel_hi:[1,0,1]
	v_pk_fma_f32 v[122:123], v[170:171], s[26:27], v[122:123] op_sel_hi:[1,0,1]
	v_pk_add_f32 v[120:121], v[212:213], v[120:121]
	v_pk_add_f32 v[122:123], v[214:215], v[122:123]
	v_cvt_pk_bf16_f32 v138, v120, v121
	v_cvt_pk_bf16_f32 v139, v122, v123
	v_lshlrev_b32_e32 v168, 16, v138
	v_and_b32_e32 v169, 0xffff0000, v138
	v_lshlrev_b32_e32 v170, 16, v139
	v_and_b32_e32 v171, 0xffff0000, v139
	v_add_f32_e32 v134, v134, v168
	v_fmac_f32_e32 v135, v168, v168
	v_add_f32_e32 v134, v134, v169
	v_fmac_f32_e32 v135, v169, v169
	v_add_f32_e32 v134, v134, v170
	v_fmac_f32_e32 v135, v170, v170
	v_add_f32_e32 v134, v134, v171
	v_fmac_f32_e32 v135, v171, v171
	v_permlane16_swap_b32_e32 v136, v138
	v_permlane16_swap_b32_e32 v137, v139
	global_store_dwordx4 v132, v[136:139], s[14:15]
	s_waitcnt vmcnt(14)
; template <int EPI>
; __device__ __forceinline__ void gemm_phase(const u16* __restrict__ A, const u16* __restrict__ Bt, const int K,
;                                            const int nN, char* shm, const EpiArgs& ea) {
;     ...
;               float rs = 0.f, rq = 0.f;
; #pragma unroll
;               for (int bj = 0; bj < 2; ++bj) {
;                 uint2 pk[2];
; #pragma unroll
;                 for (int n = 0; n < 2; ++n) {
;                   const int col = cb + bj * 128 + n * 16;
;                   f32x4 c = acc[ai][bj][m][n];
;                   float h[4];
;                   if (EPI == EPI_FFN1) {
;                     float4 rv = *(const float4*)(ea.res + (size_t)row * DM + col);
;                     h[0] = rv.x; h[1] = rv.y; h[2] = rv.z; h[3] = rv.w;
;                   } else {
;                     uint2 yv = *(const uint2*)((const char*)ea.yb + tl_off(row, col, DM >> 6));
;                     float4 gv = *(const float4*)(ea.lng + col);
;                     float4 bv = *(const float4*)(ea.lnb + col);
;                     h[0] = (bf_lo(yv.x) - mu) * rstd * gv.x + bv.x; h[1] = (bf_hi(yv.x) - mu) * rstd * gv.y + bv.y;
;                     h[2] = (bf_lo(yv.y) - mu) * rstd * gv.z + bv.z; h[3] = (bf_hi(yv.y) - mu) * rstd * gv.w + bv.w;
;                   }
;                   float y[4];
;                   if (EPI == EPI_OUT) {
;                     float4 bo = *(const float4*)(ea.bias + col);
;                     y[0] = ALPHA * h[0] + c[0] + bo.x; y[1] = ALPHA * h[1] + c[1] + bo.y;
;                     y[2] = ALPHA * h[2] + c[2] + bo.z; y[3] = ALPHA * h[3] + c[3] + bo.w;
;                   } else {
; #pragma unroll
;                     for (int j = 0; j < 4; ++j) y[j] = ALPHA * h[j] + 0.5f * c[j];
;                   }
;                   if (EPI == EPI_FFN2) {
;                     *(float4*)(ea.outf + (size_t)row * DM + col) = make_float4(y[0], y[1], y[2], y[3]);
;                   } else {
;                     pk[n] = make_uint2(pack2(y[0], y[1]), pack2(y[2], y[3]));
;                     float q0 = bf_lo(pk[n].x), q1 = bf_hi(pk[n].x), q2 = bf_lo(pk[n].y), q3 = bf_hi(pk[n].y);
;                     rs += (q0 + q1) + (q2 + q3);
;                     rq += (q0 * q0 + q1 * q1) + (q2 * q2 + q3 * q3);
;                   }
;                 }
;                 if (EPI != EPI_FFN2) {
	v_lshlrev_b32_e32 v168, 16, v228
	v_and_b32_e32 v169, 0xffff0000, v228
	v_lshlrev_b32_e32 v170, 16, v229
	v_and_b32_e32 v171, 0xffff0000, v229
	v_pk_add_f32 v[168:169], v[168:169], v[156:157] op_sel_hi:[1,0] neg_lo:[0,1] neg_hi:[0,1]
	v_pk_add_f32 v[170:171], v[170:171], v[156:157] op_sel_hi:[1,0] neg_lo:[0,1] neg_hi:[0,1]
	v_pk_mul_f32 v[168:169], v[168:169], v[164:165] op_sel_hi:[1,0]
	v_pk_mul_f32 v[170:171], v[170:171], v[164:165] op_sel_hi:[1,0]
	v_pk_fma_f32 v[168:169], v[184:185], v[168:169], v[200:201]
	v_pk_fma_f32 v[170:171], v[186:187], v[170:171], v[202:203]
	v_pk_fma_f32 v[116:117], v[168:169], s[26:27], v[116:117] op_sel_hi:[1,0,1]
	v_pk_fma_f32 v[118:119], v[170:171], s[26:27], v[118:119] op_sel_hi:[1,0,1]
	v_pk_add_f32 v[116:117], v[216:217], v[116:117]
	v_pk_add_f32 v[118:119], v[218:219], v[118:119]
	v_cvt_pk_bf16_f32 v136, v116, v117
	v_cvt_pk_bf16_f32 v137, v118, v119
	v_lshlrev_b32_e32 v168, 16, v136
	v_and_b32_e32 v169, 0xffff0000, v136
	v_lshlrev_b32_e32 v170, 16, v137
	v_and_b32_e32 v171, 0xffff0000, v137
	v_add_f32_e32 v134, v134, v168
	v_fmac_f32_e32 v135, v168, v168
	v_add_f32_e32 v134, v134, v169
	v_fmac_f32_e32 v135, v169, v169
	v_add_f32_e32 v134, v134, v170
	v_fmac_f32_e32 v135, v170, v170
	v_add_f32_e32 v134, v134, v171
	v_fmac_f32_e32 v135, v171, v171
	s_waitcnt vmcnt(13)
	v_lshlrev_b32_e32 v168, 16, v230
	v_and_b32_e32 v169, 0xffff0000, v230
	v_lshlrev_b32_e32 v170, 16, v231
	v_and_b32_e32 v171, 0xffff0000, v231
	v_pk_add_f32 v[168:169], v[168:169], v[156:157] op_sel_hi:[1,0] neg_lo:[0,1] neg_hi:[0,1]
	v_pk_add_f32 v[170:171], v[170:171], v[156:157] op_sel_hi:[1,0] neg_lo:[0,1] neg_hi:[0,1]
	v_pk_mul_f32 v[168:169], v[168:169], v[164:165] op_sel_hi:[1,0]
	v_pk_mul_f32 v[170:171], v[170:171], v[164:165] op_sel_hi:[1,0]
	v_pk_fma_f32 v[168:169], v[188:189], v[168:169], v[204:205]
	v_pk_fma_f32 v[170:171], v[190:191], v[170:171], v[206:207]
	v_pk_fma_f32 v[112:113], v[168:169], s[26:27], v[112:113] op_sel_hi:[1,0,1]
	v_pk_fma_f32 v[114:115], v[170:171], s[26:27], v[114:115] op_sel_hi:[1,0,1]
	v_pk_add_f32 v[112:113], v[220:221], v[112:113]
	v_pk_add_f32 v[114:115], v[222:223], v[114:115]
	v_cvt_pk_bf16_f32 v138, v112, v113
	v_cvt_pk_bf16_f32 v139, v114, v115
	v_lshlrev_b32_e32 v168, 16, v138
	v_and_b32_e32 v169, 0xffff0000, v138
	v_lshlrev_b32_e32 v170, 16, v139
	v_and_b32_e32 v171, 0xffff0000, v139
	v_add_f32_e32 v134, v134, v168
	v_fmac_f32_e32 v135, v168, v168
	v_add_f32_e32 v134, v134, v169
	v_fmac_f32_e32 v135, v169, v169
	v_add_f32_e32 v134, v134, v170
	v_fmac_f32_e32 v135, v170, v170
	v_add_f32_e32 v134, v134, v171
	v_fmac_f32_e32 v135, v171, v171
	v_permlane16_swap_b32_e32 v136, v138
	v_permlane16_swap_b32_e32 v137, v139
	v_add_u32_e32 v133, 0x8000, v132
	global_store_dwordx4 v133, v[136:139], s[14:15]
	global_load_dwordx2 v[156:157], v175, s[6:7] offset:1024
	v_add_u32_e32 v130, 0x84000, v172
	global_load_dwordx2 v[224:225], v130, s[14:15]
	v_add_u32_e32 v131, 0x84000, v173
	global_load_dwordx2 v[226:227], v131, s[14:15]
	v_add_u32_e32 v130, 0x8c000, v172
	global_load_dwordx2 v[228:229], v130, s[14:15]
	v_add_u32_e32 v131, 0x8c000, v173
	global_load_dwordx2 v[230:231], v131, s[14:15]
	v_mov_b32_e32 v140, v134
	v_mov_b32_e32 v141, v135
	s_nop 0
	v_permlane16_swap_b32_e32 v134, v140
	v_permlane16_swap_b32_e32 v135, v141
	v_add_f32_e32 v134, v134, v140
	v_add_f32_e32 v135, v135, v141
	v_mov_b32_e32 v140, v134
	v_mov_b32_e32 v141, v135
	s_nop 0
	v_permlane32_swap_b32_e32 v134, v140
	v_permlane32_swap_b32_e32 v135, v141
	v_add_f32_e32 v134, v134, v140
	v_add_f32_e32 v135, v135, v141
	s_and_saveexec_b64 s[10:11], s[4:5]
	global_atomic_add_f32 v175, v134, s[12:13]
	global_atomic_add_f32 v175, v135, s[12:13] offset:4
	s_or_b64 exec, exec, s[10:11]
	v_pk_mul_f32 v[158:159], v[158:159], s[24:25] op_sel_hi:[1,0]
	v_add_u32_e32 v132, 0x800, v128
	v_fma_f32 v166, -v158, v158, v159
	v_max_f32_e32 v166, 0, v166
	v_add_f32_e32 v166, 0x3727c5ac, v166
	v_rsq_f32_e32 v166, v166
	v_mov_b32_e32 v134, 0
	v_mov_b32_e32 v135, 0
	s_waitcnt vmcnt(20)
	v_lshlrev_b32_e32 v168, 16, v232
	v_and_b32_e32 v169, 0xffff0000, v232
	v_lshlrev_b32_e32 v170, 16, v233
	v_and_b32_e32 v171, 0xffff0000, v233
	v_pk_add_f32 v[168:169], v[168:169], v[158:159] op_sel_hi:[1,0] neg_lo:[0,1] neg_hi:[0,1]
	v_pk_add_f32 v[170:171], v[170:171], v[158:159] op_sel_hi:[1,0] neg_lo:[0,1] neg_hi:[0,1]
	v_pk_mul_f32 v[168:169], v[168:169], v[166:167] op_sel_hi:[1,0]
	v_pk_mul_f32 v[170:171], v[170:171], v[166:167] op_sel_hi:[1,0]
	v_pk_fma_f32 v[168:169], v[176:177], v[168:169], v[192:193]
	v_pk_fma_f32 v[170:171], v[178:179], v[170:171], v[194:195]
	v_pk_fma_f32 v[104:105], v[168:169], s[26:27], v[104:105] op_sel_hi:[1,0,1]
	v_pk_fma_f32 v[106:107], v[170:171], s[26:27], v[106:107] op_sel_hi:[1,0,1]
	v_pk_add_f32 v[104:105], v[208:209], v[104:105]
	v_pk_add_f32 v[106:107], v[210:211], v[106:107]
	v_cvt_pk_bf16_f32 v136, v104, v105
	v_cvt_pk_bf16_f32 v137, v106, v107
	v_lshlrev_b32_e32 v168, 16, v136
	v_and_b32_e32 v169, 0xffff0000, v136
	v_lshlrev_b32_e32 v170, 16, v137
	v_and_b32_e32 v171, 0xffff0000, v137
	v_add_f32_e32 v134, v134, v168
	v_fmac_f32_e32 v135, v168, v168
	v_add_f32_e32 v134, v134, v169
	v_fmac_f32_e32 v135, v169, v169
	v_add_f32_e32 v134, v134, v170
	v_fmac_f32_e32 v135, v170, v170
	v_add_f32_e32 v134, v134, v171
	v_fmac_f32_e32 v135, v171, v171
	s_waitcnt vmcnt(19)
; template <int EPI>
; __device__ __forceinline__ void gemm_phase(const u16* __restrict__ A, const u16* __restrict__ Bt, const int K,
;                                            const int nN, char* shm, const EpiArgs& ea) {
;     ...
;               float rs = 0.f, rq = 0.f;
; #pragma unroll
;               for (int bj = 0; bj < 2; ++bj) {
;                 uint2 pk[2];
; #pragma unroll
;                 for (int n = 0; n < 2; ++n) {
;                   const int col = cb + bj * 128 + n * 16;
;                   f32x4 c = acc[ai][bj][m][n];
;                   float h[4];
;                   if (EPI == EPI_FFN1) {
;                     float4 rv = *(const float4*)(ea.res + (size_t)row * DM + col);
;                     h[0] = rv.x; h[1] = rv.y; h[2] = rv.z; h[3] = rv.w;
;                   } else {
;                     uint2 yv = *(const uint2*)((const char*)ea.yb + tl_off(row, col, DM >> 6));
;                     float4 gv = *(const float4*)(ea.lng + col);
;                     float4 bv = *(const float4*)(ea.lnb + col);
;                     h[0] = (bf_lo(yv.x) - mu) * rstd * gv.x + bv.x; h[1] = (bf_hi(yv.x) - mu) * rstd * gv.y + bv.y;
;                     h[2] = (bf_lo(yv.y) - mu) * rstd * gv.z + bv.z; h[3] = (bf_hi(yv.y) - mu) * rstd * gv.w + bv.w;
;                   }
;                   float y[4];
;                   if (EPI == EPI_OUT) {
;                     float4 bo = *(const float4*)(ea.bias + col);
;                     y[0] = ALPHA * h[0] + c[0] + bo.x; y[1] = ALPHA * h[1] + c[1] + bo.y;
;                     y[2] = ALPHA * h[2] + c[2] + bo.z; y[3] = ALPHA * h[3] + c[3] + bo.w;
;                   } else {
; #pragma unroll
;                     for (int j = 0; j < 4; ++j) y[j] = ALPHA * h[j] + 0.5f * c[j];
;                   }
;                   if (EPI == EPI_FFN2) {
;                     *(float4*)(ea.outf + (size_t)row * DM + col) = make_float4(y[0], y[1], y[2], y[3]);
;                   } else {
;                     pk[n] = make_uint2(pack2(y[0], y[1]), pack2(y[2], y[3]));
;                     float q0 = bf_lo(pk[n].x), q1 = bf_hi(pk[n].x), q2 = bf_lo(pk[n].y), q3 = bf_hi(pk[n].y);
;                     rs += (q0 + q1) + (q2 + q3);
;                     rq += (q0 * q0 + q1 * q1) + (q2 * q2 + q3 * q3);
;                   }
;                 }
;                 if (EPI != EPI_FFN2) {
	v_lshlrev_b32_e32 v168, 16, v234
	v_and_b32_e32 v169, 0xffff0000, v234
	v_lshlrev_b32_e32 v170, 16, v235
	v_and_b32_e32 v171, 0xffff0000, v235
	v_pk_add_f32 v[168:169], v[168:169], v[158:159] op_sel_hi:[1,0] neg_lo:[0,1] neg_hi:[0,1]
	v_pk_add_f32 v[170:171], v[170:171], v[158:159] op_sel_hi:[1,0] neg_lo:[0,1] neg_hi:[0,1]
	v_pk_mul_f32 v[168:169], v[168:169], v[166:167] op_sel_hi:[1,0]
	v_pk_mul_f32 v[170:171], v[170:171], v[166:167] op_sel_hi:[1,0]
	v_pk_fma_f32 v[168:169], v[180:181], v[168:169], v[196:197]
	v_pk_fma_f32 v[170:171], v[182:183], v[170:171], v[198:199]
	v_pk_fma_f32 v[108:109], v[168:169], s[26:27], v[108:109] op_sel_hi:[1,0,1]
	v_pk_fma_f32 v[110:111], v[170:171], s[26:27], v[110:111] op_sel_hi:[1,0,1]
	v_pk_add_f32 v[108:109], v[212:213], v[108:109]
	v_pk_add_f32 v[110:111], v[214:215], v[110:111]
	v_cvt_pk_bf16_f32 v138, v108, v109
	v_cvt_pk_bf16_f32 v139, v110, v111
	v_lshlrev_b32_e32 v168, 16, v138
	v_and_b32_e32 v169, 0xffff0000, v138
	v_lshlrev_b32_e32 v170, 16, v139
	v_and_b32_e32 v171, 0xffff0000, v139
	v_add_f32_e32 v134, v134, v168
	v_fmac_f32_e32 v135, v168, v168
	v_add_f32_e32 v134, v134, v169
	v_fmac_f32_e32 v135, v169, v169
	v_add_f32_e32 v134, v134, v170
	v_fmac_f32_e32 v135, v170, v170
	v_add_f32_e32 v134, v134, v171
	v_fmac_f32_e32 v135, v171, v171
	v_permlane16_swap_b32_e32 v136, v138
	v_permlane16_swap_b32_e32 v137, v139
	global_store_dwordx4 v132, v[136:139], s[14:15]
	s_waitcnt vmcnt(19)
	v_lshlrev_b32_e32 v168, 16, v236
	v_and_b32_e32 v169, 0xffff0000, v236
	v_lshlrev_b32_e32 v170, 16, v237
	v_and_b32_e32 v171, 0xffff0000, v237
	v_pk_add_f32 v[168:169], v[168:169], v[158:159] op_sel_hi:[1,0] neg_lo:[0,1] neg_hi:[0,1]
	v_pk_add_f32 v[170:171], v[170:171], v[158:159] op_sel_hi:[1,0] neg_lo:[0,1] neg_hi:[0,1]
	v_pk_mul_f32 v[168:169], v[168:169], v[166:167] op_sel_hi:[1,0]
	v_pk_mul_f32 v[170:171], v[170:171], v[166:167] op_sel_hi:[1,0]
	v_pk_fma_f32 v[168:169], v[184:185], v[168:169], v[200:201]
	v_pk_fma_f32 v[170:171], v[186:187], v[170:171], v[202:203]
	v_pk_fma_f32 v[100:101], v[168:169], s[26:27], v[100:101] op_sel_hi:[1,0,1]
	v_pk_fma_f32 v[102:103], v[170:171], s[26:27], v[102:103] op_sel_hi:[1,0,1]
	v_pk_add_f32 v[100:101], v[216:217], v[100:101]
	v_pk_add_f32 v[102:103], v[218:219], v[102:103]
	v_cvt_pk_bf16_f32 v136, v100, v101
	v_cvt_pk_bf16_f32 v137, v102, v103
	v_lshlrev_b32_e32 v168, 16, v136
	v_and_b32_e32 v169, 0xffff0000, v136
	v_lshlrev_b32_e32 v170, 16, v137
	v_and_b32_e32 v171, 0xffff0000, v137
	v_add_f32_e32 v134, v134, v168
	v_fmac_f32_e32 v135, v168, v168
	v_add_f32_e32 v134, v134, v169
	v_fmac_f32_e32 v135, v169, v169
	v_add_f32_e32 v134, v134, v170
	v_fmac_f32_e32 v135, v170, v170
	v_add_f32_e32 v134, v134, v171
	v_fmac_f32_e32 v135, v171, v171
	s_waitcnt vmcnt(18)
	v_lshlrev_b32_e32 v168, 16, v238
	v_and_b32_e32 v169, 0xffff0000, v238
	v_lshlrev_b32_e32 v170, 16, v239
	v_and_b32_e32 v171, 0xffff0000, v239
	v_pk_add_f32 v[168:169], v[168:169], v[158:159] op_sel_hi:[1,0] neg_lo:[0,1] neg_hi:[0,1]
	v_pk_add_f32 v[170:171], v[170:171], v[158:159] op_sel_hi:[1,0] neg_lo:[0,1] neg_hi:[0,1]
	v_pk_mul_f32 v[168:169], v[168:169], v[166:167] op_sel_hi:[1,0]
	v_pk_mul_f32 v[170:171], v[170:171], v[166:167] op_sel_hi:[1,0]
	v_pk_fma_f32 v[168:169], v[188:189], v[168:169], v[204:205]
	v_pk_fma_f32 v[170:171], v[190:191], v[170:171], v[206:207]
	v_pk_fma_f32 v[96:97], v[168:169], s[26:27], v[96:97] op_sel_hi:[1,0,1]
	v_pk_fma_f32 v[98:99], v[170:171], s[26:27], v[98:99] op_sel_hi:[1,0,1]
	v_pk_add_f32 v[96:97], v[220:221], v[96:97]
	v_pk_add_f32 v[98:99], v[222:223], v[98:99]
	v_cvt_pk_bf16_f32 v138, v96, v97
	v_cvt_pk_bf16_f32 v139, v98, v99
	v_lshlrev_b32_e32 v168, 16, v138
	v_and_b32_e32 v169, 0xffff0000, v138
	v_lshlrev_b32_e32 v170, 16, v139
	v_and_b32_e32 v171, 0xffff0000, v139
	v_add_f32_e32 v134, v134, v168
	v_fmac_f32_e32 v135, v168, v168
	v_add_f32_e32 v134, v134, v169
	v_fmac_f32_e32 v135, v169, v169
	v_add_f32_e32 v134, v134, v170
	v_fmac_f32_e32 v135, v170, v170
	v_add_f32_e32 v134, v134, v171
	v_fmac_f32_e32 v135, v171, v171
	v_permlane16_swap_b32_e32 v136, v138
	v_permlane16_swap_b32_e32 v137, v139
	v_add_u32_e32 v133, 0x8000, v132
	global_store_dwordx4 v133, v[136:139], s[14:15]
	global_load_dwordx2 v[158:159], v175, s[6:7] offset:1152
	v_add_u32_e32 v130, 0x84800, v172
	global_load_dwordx2 v[232:233], v130, s[14:15]
	v_add_u32_e32 v131, 0x84800, v173
	global_load_dwordx2 v[234:235], v131, s[14:15]
	v_add_u32_e32 v130, 0x8c800, v172
	global_load_dwordx2 v[236:237], v130, s[14:15]
	v_add_u32_e32 v131, 0x8c800, v173
	global_load_dwordx2 v[238:239], v131, s[14:15]
	v_mov_b32_e32 v140, v134
	v_mov_b32_e32 v141, v135
	s_nop 0
	v_permlane16_swap_b32_e32 v134, v140
	v_permlane16_swap_b32_e32 v135, v141
	v_add_f32_e32 v134, v134, v140
	v_add_f32_e32 v135, v135, v141
	v_mov_b32_e32 v140, v134
	v_mov_b32_e32 v141, v135
	s_nop 0
	v_permlane32_swap_b32_e32 v134, v140
	v_permlane32_swap_b32_e32 v135, v141
	v_add_f32_e32 v134, v134, v140
	v_add_f32_e32 v135, v135, v141
	s_and_saveexec_b64 s[10:11], s[4:5]
	global_atomic_add_f32 v175, v134, s[12:13] offset:128
	global_atomic_add_f32 v175, v135, s[12:13] offset:132
	s_or_b64 exec, exec, s[10:11]
	v_pk_mul_f32 v[160:161], v[160:161], s[24:25] op_sel_hi:[1,0]
	v_add_u32_e32 v132, 0x1000, v128
	v_fma_f32 v164, -v160, v160, v161
	v_max_f32_e32 v164, 0, v164
	v_add_f32_e32 v164, 0x3727c5ac, v164
	v_rsq_f32_e32 v164, v164
	v_mov_b32_e32 v134, 0
	v_mov_b32_e32 v135, 0
	s_waitcnt vmcnt(25)
; template <int EPI>
; __device__ __forceinline__ void gemm_phase(const u16* __restrict__ A, const u16* __restrict__ Bt, const int K,
;                                            const int nN, char* shm, const EpiArgs& ea) {
;     ...
;               float rs = 0.f, rq = 0.f;
; #pragma unroll
;               for (int bj = 0; bj < 2; ++bj) {
;                 uint2 pk[2];
; #pragma unroll
;                 for (int n = 0; n < 2; ++n) {
;                   const int col = cb + bj * 128 + n * 16;
;                   f32x4 c = acc[ai][bj][m][n];
;                   float h[4];
;                   if (EPI == EPI_FFN1) {
;                     float4 rv = *(const float4*)(ea.res + (size_t)row * DM + col);
;                     h[0] = rv.x; h[1] = rv.y; h[2] = rv.z; h[3] = rv.w;
;                   } else {
;                     uint2 yv = *(const uint2*)((const char*)ea.yb + tl_off(row, col, DM >> 6));
;                     float4 gv = *(const float4*)(ea.lng + col);
;                     float4 bv = *(const float4*)(ea.lnb + col);
;                     h[0] = (bf_lo(yv.x) - mu) * rstd * gv.x + bv.x; h[1] = (bf_hi(yv.x) - mu) * rstd * gv.y + bv.y;
;                     h[2] = (bf_lo(yv.y) - mu) * rstd * gv.z + bv.z; h[3] = (bf_hi(yv.y) - mu) * rstd * gv.w + bv.w;
;                   }
;                   float y[4];
;                   if (EPI == EPI_OUT) {
;                     float4 bo = *(const float4*)(ea.bias + col);
;                     y[0] = ALPHA * h[0] + c[0] + bo.x; y[1] = ALPHA * h[1] + c[1] + bo.y;
;                     y[2] = ALPHA * h[2] + c[2] + bo.z; y[3] = ALPHA * h[3] + c[3] + bo.w;
;                   } else {
; #pragma unroll
;                     for (int j = 0; j < 4; ++j) y[j] = ALPHA * h[j] + 0.5f * c[j];
;                   }
;                   if (EPI == EPI_FFN2) {
;                     *(float4*)(ea.outf + (size_t)row * DM + col) = make_float4(y[0], y[1], y[2], y[3]);
;                   } else {
;                     pk[n] = make_uint2(pack2(y[0], y[1]), pack2(y[2], y[3]));
;                     float q0 = bf_lo(pk[n].x), q1 = bf_hi(pk[n].x), q2 = bf_lo(pk[n].y), q3 = bf_hi(pk[n].y);
;                     rs += (q0 + q1) + (q2 + q3);
;                     rq += (q0 * q0 + q1 * q1) + (q2 * q2 + q3 * q3);
;                   }
;                 }
;                 if (EPI != EPI_FFN2) {
	v_lshlrev_b32_e32 v168, 16, v240
	v_and_b32_e32 v169, 0xffff0000, v240
	v_lshlrev_b32_e32 v170, 16, v241
	v_and_b32_e32 v171, 0xffff0000, v241
	v_pk_add_f32 v[168:169], v[168:169], v[160:161] op_sel_hi:[1,0] neg_lo:[0,1] neg_hi:[0,1]
	v_pk_add_f32 v[170:171], v[170:171], v[160:161] op_sel_hi:[1,0] neg_lo:[0,1] neg_hi:[0,1]
	v_pk_mul_f32 v[168:169], v[168:169], v[164:165] op_sel_hi:[1,0]
	v_pk_mul_f32 v[170:171], v[170:171], v[164:165] op_sel_hi:[1,0]
	v_pk_fma_f32 v[168:169], v[176:177], v[168:169], v[192:193]
	v_pk_fma_f32 v[170:171], v[178:179], v[170:171], v[194:195]
	v_pk_fma_f32 v[88:89], v[168:169], s[26:27], v[88:89] op_sel_hi:[1,0,1]
	v_pk_fma_f32 v[90:91], v[170:171], s[26:27], v[90:91] op_sel_hi:[1,0,1]
	v_pk_add_f32 v[88:89], v[208:209], v[88:89]
	v_pk_add_f32 v[90:91], v[210:211], v[90:91]
	v_cvt_pk_bf16_f32 v136, v88, v89
	v_cvt_pk_bf16_f32 v137, v90, v91
	v_lshlrev_b32_e32 v168, 16, v136
	v_and_b32_e32 v169, 0xffff0000, v136
	v_lshlrev_b32_e32 v170, 16, v137
	v_and_b32_e32 v171, 0xffff0000, v137
	v_add_f32_e32 v134, v134, v168
	v_fmac_f32_e32 v135, v168, v168
	v_add_f32_e32 v134, v134, v169
	v_fmac_f32_e32 v135, v169, v169
	v_add_f32_e32 v134, v134, v170
	v_fmac_f32_e32 v135, v170, v170
	v_add_f32_e32 v134, v134, v171
	v_fmac_f32_e32 v135, v171, v171
	s_waitcnt vmcnt(24)
	v_lshlrev_b32_e32 v168, 16, v242
	v_and_b32_e32 v169, 0xffff0000, v242
	v_lshlrev_b32_e32 v170, 16, v243
	v_and_b32_e32 v171, 0xffff0000, v243
	v_pk_add_f32 v[168:169], v[168:169], v[160:161] op_sel_hi:[1,0] neg_lo:[0,1] neg_hi:[0,1]
	v_pk_add_f32 v[170:171], v[170:171], v[160:161] op_sel_hi:[1,0] neg_lo:[0,1] neg_hi:[0,1]
	v_pk_mul_f32 v[168:169], v[168:169], v[164:165] op_sel_hi:[1,0]
	v_pk_mul_f32 v[170:171], v[170:171], v[164:165] op_sel_hi:[1,0]
	v_pk_fma_f32 v[168:169], v[180:181], v[168:169], v[196:197]
	v_pk_fma_f32 v[170:171], v[182:183], v[170:171], v[198:199]
	v_pk_fma_f32 v[92:93], v[168:169], s[26:27], v[92:93] op_sel_hi:[1,0,1]
	v_pk_fma_f32 v[94:95], v[170:171], s[26:27], v[94:95] op_sel_hi:[1,0,1]
	v_pk_add_f32 v[92:93], v[212:213], v[92:93]
	v_pk_add_f32 v[94:95], v[214:215], v[94:95]
	v_cvt_pk_bf16_f32 v138, v92, v93
	v_cvt_pk_bf16_f32 v139, v94, v95
	v_lshlrev_b32_e32 v168, 16, v138
	v_and_b32_e32 v169, 0xffff0000, v138
	v_lshlrev_b32_e32 v170, 16, v139
	v_and_b32_e32 v171, 0xffff0000, v139
	v_add_f32_e32 v134, v134, v168
	v_fmac_f32_e32 v135, v168, v168
	v_add_f32_e32 v134, v134, v169
	v_fmac_f32_e32 v135, v169, v169
	v_add_f32_e32 v134, v134, v170
	v_fmac_f32_e32 v135, v170, v170
	v_add_f32_e32 v134, v134, v171
	v_fmac_f32_e32 v135, v171, v171
	v_permlane16_swap_b32_e32 v136, v138
	v_permlane16_swap_b32_e32 v137, v139
	global_store_dwordx4 v132, v[136:139], s[14:15]
	s_waitcnt vmcnt(24)
	v_lshlrev_b32_e32 v168, 16, v246
	v_and_b32_e32 v169, 0xffff0000, v246
	v_lshlrev_b32_e32 v170, 16, v247
	v_and_b32_e32 v171, 0xffff0000, v247
	v_pk_add_f32 v[168:169], v[168:169], v[160:161] op_sel_hi:[1,0] neg_lo:[0,1] neg_hi:[0,1]
	v_pk_add_f32 v[170:171], v[170:171], v[160:161] op_sel_hi:[1,0] neg_lo:[0,1] neg_hi:[0,1]
	v_pk_mul_f32 v[168:169], v[168:169], v[164:165] op_sel_hi:[1,0]
	v_pk_mul_f32 v[170:171], v[170:171], v[164:165] op_sel_hi:[1,0]
	v_pk_fma_f32 v[168:169], v[184:185], v[168:169], v[200:201]
	v_pk_fma_f32 v[170:171], v[186:187], v[170:171], v[202:203]
	v_pk_fma_f32 v[84:85], v[168:169], s[26:27], v[84:85] op_sel_hi:[1,0,1]
	v_pk_fma_f32 v[86:87], v[170:171], s[26:27], v[86:87] op_sel_hi:[1,0,1]
	v_pk_add_f32 v[84:85], v[216:217], v[84:85]
	v_pk_add_f32 v[86:87], v[218:219], v[86:87]
	v_cvt_pk_bf16_f32 v136, v84, v85
	v_cvt_pk_bf16_f32 v137, v86, v87
	v_lshlrev_b32_e32 v168, 16, v136
	v_and_b32_e32 v169, 0xffff0000, v136
	v_lshlrev_b32_e32 v170, 16, v137
	v_and_b32_e32 v171, 0xffff0000, v137
	v_add_f32_e32 v134, v134, v168
	v_fmac_f32_e32 v135, v168, v168
	v_add_f32_e32 v134, v134, v169
	v_fmac_f32_e32 v135, v169, v169
	v_add_f32_e32 v134, v134, v170
	v_fmac_f32_e32 v135, v170, v170
	v_add_f32_e32 v134, v134, v171
	v_fmac_f32_e32 v135, v171, v171
	s_waitcnt vmcnt(23)
	v_lshlrev_b32_e32 v168, 16, v248
	v_and_b32_e32 v169, 0xffff0000, v248
	v_lshlrev_b32_e32 v170, 16, v249
	v_and_b32_e32 v171, 0xffff0000, v249
	v_pk_add_f32 v[168:169], v[168:169], v[160:161] op_sel_hi:[1,0] neg_lo:[0,1] neg_hi:[0,1]
	v_pk_add_f32 v[170:171], v[170:171], v[160:161] op_sel_hi:[1,0] neg_lo:[0,1] neg_hi:[0,1]
	v_pk_mul_f32 v[168:169], v[168:169], v[164:165] op_sel_hi:[1,0]
	v_pk_mul_f32 v[170:171], v[170:171], v[164:165] op_sel_hi:[1,0]
	v_pk_fma_f32 v[168:169], v[188:189], v[168:169], v[204:205]
	v_pk_fma_f32 v[170:171], v[190:191], v[170:171], v[206:207]
	v_pk_fma_f32 v[80:81], v[168:169], s[26:27], v[80:81] op_sel_hi:[1,0,1]
	v_pk_fma_f32 v[82:83], v[170:171], s[26:27], v[82:83] op_sel_hi:[1,0,1]
	v_pk_add_f32 v[80:81], v[220:221], v[80:81]
	v_pk_add_f32 v[82:83], v[222:223], v[82:83]
	v_cvt_pk_bf16_f32 v138, v80, v81
	v_cvt_pk_bf16_f32 v139, v82, v83
	v_lshlrev_b32_e32 v168, 16, v138
	v_and_b32_e32 v169, 0xffff0000, v138
	v_lshlrev_b32_e32 v170, 16, v139
	v_and_b32_e32 v171, 0xffff0000, v139
	v_add_f32_e32 v134, v134, v168
	v_fmac_f32_e32 v135, v168, v168
	v_add_f32_e32 v134, v134, v169
	v_fmac_f32_e32 v135, v169, v169
	v_add_f32_e32 v134, v134, v170
	v_fmac_f32_e32 v135, v170, v170
	v_add_f32_e32 v134, v134, v171
	v_fmac_f32_e32 v135, v171, v171
	v_permlane16_swap_b32_e32 v136, v138
	v_permlane16_swap_b32_e32 v137, v139
	v_add_u32_e32 v133, 0x8000, v132
	global_store_dwordx4 v133, v[136:139], s[14:15]
	global_load_dwordx2 v[160:161], v175, s[6:7] offset:1280
	v_add_u32_e32 v130, 0x85000, v172
	global_load_dwordx2 v[240:241], v130, s[14:15]
	v_add_u32_e32 v131, 0x85000, v173
	global_load_dwordx2 v[242:243], v131, s[14:15]
	v_add_u32_e32 v130, 0x8d000, v172
	global_load_dwordx2 v[246:247], v130, s[14:15]
	v_add_u32_e32 v131, 0x8d000, v173
	global_load_dwordx2 v[248:249], v131, s[14:15]
	v_mov_b32_e32 v140, v134
	v_mov_b32_e32 v141, v135
	s_nop 0
	v_permlane16_swap_b32_e32 v134, v140
	v_permlane16_swap_b32_e32 v135, v141
	v_add_f32_e32 v134, v134, v140
	v_add_f32_e32 v135, v135, v141
	v_mov_b32_e32 v140, v134
	v_mov_b32_e32 v141, v135
	s_nop 0
	v_permlane32_swap_b32_e32 v134, v140
	v_permlane32_swap_b32_e32 v135, v141
	v_add_f32_e32 v134, v134, v140
	v_add_f32_e32 v135, v135, v141
	s_and_saveexec_b64 s[10:11], s[4:5]
	global_atomic_add_f32 v175, v134, s[12:13] offset:256
	global_atomic_add_f32 v175, v135, s[12:13] offset:260
	s_or_b64 exec, exec, s[10:11]
	v_pk_mul_f32 v[162:163], v[162:163], s[24:25] op_sel_hi:[1,0]
	v_add_u32_e32 v132, 0x1800, v128
	v_fma_f32 v166, -v162, v162, v163
	v_max_f32_e32 v166, 0, v166
	v_add_f32_e32 v166, 0x3727c5ac, v166
	v_rsq_f32_e32 v166, v166
	v_mov_b32_e32 v134, 0
	v_mov_b32_e32 v135, 0
	s_waitcnt vmcnt(30)
; template <int EPI>
; __device__ __forceinline__ void gemm_phase(const u16* __restrict__ A, const u16* __restrict__ Bt, const int K,
;                                            const int nN, char* shm, const EpiArgs& ea) {
;     ...
;               float mu = 0.f, rstd = 1.f;
;               if (EPI != EPI_FFN1) row_stats(ea.st_in, row, mu, rstd);
;               float rs = 0.f, rq = 0.f;
; #pragma unroll
;               for (int bj = 0; bj < 2; ++bj) {
;                 uint2 pk[2];
; #pragma unroll
;                 for (int n = 0; n < 2; ++n) {
;                   const int col = cb + bj * 128 + n * 16;
;                   f32x4 c = acc[ai][bj][m][n];
;                   float h[4];
;                   if (EPI == EPI_FFN1) {
;                     float4 rv = *(const float4*)(ea.res + (size_t)row * DM + col);
;                     h[0] = rv.x; h[1] = rv.y; h[2] = rv.z; h[3] = rv.w;
;                   } else {
;                     uint2 yv = *(const uint2*)((const char*)ea.yb + tl_off(row, col, DM >> 6));
;                     float4 gv = *(const float4*)(ea.lng + col);
;                     float4 bv = *(const float4*)(ea.lnb + col);
;                     h[0] = (bf_lo(yv.x) - mu) * rstd * gv.x + bv.x; h[1] = (bf_hi(yv.x) - mu) * rstd * gv.y + bv.y;
;                     h[2] = (bf_lo(yv.y) - mu) * rstd * gv.z + bv.z; h[3] = (bf_hi(yv.y) - mu) * rstd * gv.w + bv.w;
;                   }
;                   float y[4];
;                   if (EPI == EPI_OUT) {
;                     float4 bo = *(const float4*)(ea.bias + col);
;                     y[0] = ALPHA * h[0] + c[0] + bo.x; y[1] = ALPHA * h[1] + c[1] + bo.y;
;                     y[2] = ALPHA * h[2] + c[2] + bo.z; y[3] = ALPHA * h[3] + c[3] + bo.w;
;                   } else {
; #pragma unroll
;                     for (int j = 0; j < 4; ++j) y[j] = ALPHA * h[j] + 0.5f * c[j];
;                   }
;                   if (EPI == EPI_FFN2) {
;                     *(float4*)(ea.outf + (size_t)row * DM + col) = make_float4(y[0], y[1], y[2], y[3]);
;                   } else {
;                     pk[n] = make_uint2(pack2(y[0], y[1]), pack2(y[2], y[3]));
;                     float q0 = bf_lo(pk[n].x), q1 = bf_hi(pk[n].x), q2 = bf_lo(pk[n].y), q3 = bf_hi(pk[n].y);
;                     rs += (q0 + q1) + (q2 + q3);
;                     rq += (q0 * q0 + q1 * q1) + (q2 * q2 + q3 * q3);
;                   }
	v_lshlrev_b32_e32 v168, 16, v250
	v_and_b32_e32 v169, 0xffff0000, v250
	v_lshlrev_b32_e32 v170, 16, v251
	v_and_b32_e32 v171, 0xffff0000, v251
	v_pk_add_f32 v[168:169], v[168:169], v[162:163] op_sel_hi:[1,0] neg_lo:[0,1] neg_hi:[0,1]
	v_pk_add_f32 v[170:171], v[170:171], v[162:163] op_sel_hi:[1,0] neg_lo:[0,1] neg_hi:[0,1]
	v_pk_mul_f32 v[168:169], v[168:169], v[166:167] op_sel_hi:[1,0]
	v_pk_mul_f32 v[170:171], v[170:171], v[166:167] op_sel_hi:[1,0]
	v_pk_fma_f32 v[168:169], v[176:177], v[168:169], v[192:193]
	v_pk_fma_f32 v[170:171], v[178:179], v[170:171], v[194:195]
	v_pk_fma_f32 v[72:73], v[168:169], s[26:27], v[72:73] op_sel_hi:[1,0,1]
	v_pk_fma_f32 v[74:75], v[170:171], s[26:27], v[74:75] op_sel_hi:[1,0,1]
	v_pk_add_f32 v[72:73], v[208:209], v[72:73]
	v_pk_add_f32 v[74:75], v[210:211], v[74:75]
	v_cvt_pk_bf16_f32 v136, v72, v73
	v_cvt_pk_bf16_f32 v137, v74, v75
	v_lshlrev_b32_e32 v168, 16, v136
	v_and_b32_e32 v169, 0xffff0000, v136
	v_lshlrev_b32_e32 v170, 16, v137
	v_and_b32_e32 v171, 0xffff0000, v137
	v_add_f32_e32 v134, v134, v168
	v_fmac_f32_e32 v135, v168, v168
	v_add_f32_e32 v134, v134, v169
	v_fmac_f32_e32 v135, v169, v169
	v_add_f32_e32 v134, v134, v170
	v_fmac_f32_e32 v135, v170, v170
	v_add_f32_e32 v134, v134, v171
	v_fmac_f32_e32 v135, v171, v171
	s_waitcnt vmcnt(29)
	v_lshlrev_b32_e32 v168, 16, v252
	v_and_b32_e32 v169, 0xffff0000, v252
	v_lshlrev_b32_e32 v170, 16, v253
	v_and_b32_e32 v171, 0xffff0000, v253
	v_pk_add_f32 v[168:169], v[168:169], v[162:163] op_sel_hi:[1,0] neg_lo:[0,1] neg_hi:[0,1]
	v_pk_add_f32 v[170:171], v[170:171], v[162:163] op_sel_hi:[1,0] neg_lo:[0,1] neg_hi:[0,1]
	v_pk_mul_f32 v[168:169], v[168:169], v[166:167] op_sel_hi:[1,0]
	v_pk_mul_f32 v[170:171], v[170:171], v[166:167] op_sel_hi:[1,0]
	v_pk_fma_f32 v[168:169], v[180:181], v[168:169], v[196:197]
	v_pk_fma_f32 v[170:171], v[182:183], v[170:171], v[198:199]
	v_pk_fma_f32 v[76:77], v[168:169], s[26:27], v[76:77] op_sel_hi:[1,0,1]
	v_pk_fma_f32 v[78:79], v[170:171], s[26:27], v[78:79] op_sel_hi:[1,0,1]
	v_pk_add_f32 v[76:77], v[212:213], v[76:77]
	v_pk_add_f32 v[78:79], v[214:215], v[78:79]
	v_cvt_pk_bf16_f32 v138, v76, v77
	v_cvt_pk_bf16_f32 v139, v78, v79
	v_lshlrev_b32_e32 v168, 16, v138
	v_and_b32_e32 v169, 0xffff0000, v138
	v_lshlrev_b32_e32 v170, 16, v139
	v_and_b32_e32 v171, 0xffff0000, v139
	v_add_f32_e32 v134, v134, v168
	v_fmac_f32_e32 v135, v168, v168
	v_add_f32_e32 v134, v134, v169
	v_fmac_f32_e32 v135, v169, v169
	v_add_f32_e32 v134, v134, v170
	v_fmac_f32_e32 v135, v170, v170
	v_add_f32_e32 v134, v134, v171
	v_fmac_f32_e32 v135, v171, v171
	v_permlane16_swap_b32_e32 v136, v138
	v_permlane16_swap_b32_e32 v137, v139
	global_store_dwordx4 v132, v[136:139], s[14:15]
	s_waitcnt vmcnt(29)
	v_lshlrev_b32_e32 v168, 16, v254
	v_and_b32_e32 v169, 0xffff0000, v254
	v_lshlrev_b32_e32 v170, 16, v255
	v_and_b32_e32 v171, 0xffff0000, v255
	v_pk_add_f32 v[168:169], v[168:169], v[162:163] op_sel_hi:[1,0] neg_lo:[0,1] neg_hi:[0,1]
	v_pk_add_f32 v[170:171], v[170:171], v[162:163] op_sel_hi:[1,0] neg_lo:[0,1] neg_hi:[0,1]
	v_pk_mul_f32 v[168:169], v[168:169], v[166:167] op_sel_hi:[1,0]
	v_pk_mul_f32 v[170:171], v[170:171], v[166:167] op_sel_hi:[1,0]
	v_pk_fma_f32 v[168:169], v[184:185], v[168:169], v[200:201]
	v_pk_fma_f32 v[170:171], v[186:187], v[170:171], v[202:203]
	v_pk_fma_f32 v[68:69], v[168:169], s[26:27], v[68:69] op_sel_hi:[1,0,1]
	v_pk_fma_f32 v[70:71], v[170:171], s[26:27], v[70:71] op_sel_hi:[1,0,1]
	v_pk_add_f32 v[68:69], v[216:217], v[68:69]
	v_pk_add_f32 v[70:71], v[218:219], v[70:71]
	v_cvt_pk_bf16_f32 v136, v68, v69
	v_cvt_pk_bf16_f32 v137, v70, v71
	v_lshlrev_b32_e32 v168, 16, v136
	v_and_b32_e32 v169, 0xffff0000, v136
	v_lshlrev_b32_e32 v170, 16, v137
	v_and_b32_e32 v171, 0xffff0000, v137
	v_add_f32_e32 v134, v134, v168
	v_fmac_f32_e32 v135, v168, v168
	v_add_f32_e32 v134, v134, v169
	v_fmac_f32_e32 v135, v169, v169
	v_add_f32_e32 v134, v134, v170
	v_fmac_f32_e32 v135, v170, v170
	v_add_f32_e32 v134, v134, v171
	v_fmac_f32_e32 v135, v171, v171
	s_waitcnt vmcnt(28)
	v_lshlrev_b32_e32 v168, 16, v154
	v_and_b32_e32 v169, 0xffff0000, v154
	v_lshlrev_b32_e32 v170, 16, v155
	v_and_b32_e32 v171, 0xffff0000, v155
	v_pk_add_f32 v[168:169], v[168:169], v[162:163] op_sel_hi:[1,0] neg_lo:[0,1] neg_hi:[0,1]
	v_pk_add_f32 v[170:171], v[170:171], v[162:163] op_sel_hi:[1,0] neg_lo:[0,1] neg_hi:[0,1]
	v_pk_mul_f32 v[168:169], v[168:169], v[166:167] op_sel_hi:[1,0]
	v_pk_mul_f32 v[170:171], v[170:171], v[166:167] op_sel_hi:[1,0]
	v_pk_fma_f32 v[168:169], v[188:189], v[168:169], v[204:205]
	v_pk_fma_f32 v[170:171], v[190:191], v[170:171], v[206:207]
	v_pk_fma_f32 v[64:65], v[168:169], s[26:27], v[64:65] op_sel_hi:[1,0,1]
	v_pk_fma_f32 v[66:67], v[170:171], s[26:27], v[66:67] op_sel_hi:[1,0,1]
	v_pk_add_f32 v[64:65], v[220:221], v[64:65]
	v_pk_add_f32 v[66:67], v[222:223], v[66:67]
	v_cvt_pk_bf16_f32 v138, v64, v65
	v_cvt_pk_bf16_f32 v139, v66, v67
	v_lshlrev_b32_e32 v168, 16, v138
	v_and_b32_e32 v169, 0xffff0000, v138
	v_lshlrev_b32_e32 v170, 16, v139
	v_and_b32_e32 v171, 0xffff0000, v139
	v_add_f32_e32 v134, v134, v168
	v_fmac_f32_e32 v135, v168, v168
	v_add_f32_e32 v134, v134, v169
	v_fmac_f32_e32 v135, v169, v169
	v_add_f32_e32 v134, v134, v170
	v_fmac_f32_e32 v135, v170, v170
	v_add_f32_e32 v134, v134, v171
	v_fmac_f32_e32 v135, v171, v171
	v_permlane16_swap_b32_e32 v136, v138
	v_permlane16_swap_b32_e32 v137, v139
	v_add_u32_e32 v133, 0x8000, v132
	global_store_dwordx4 v133, v[136:139], s[14:15]
	global_load_dwordx2 v[162:163], v175, s[6:7] offset:1408
	v_add_u32_e32 v130, 0x85800, v172
	global_load_dwordx2 v[250:251], v130, s[14:15]
	v_add_u32_e32 v131, 0x85800, v173
	global_load_dwordx2 v[252:253], v131, s[14:15]
	v_add_u32_e32 v130, 0x8d800, v172
	global_load_dwordx2 v[254:255], v130, s[14:15]
	v_add_u32_e32 v131, 0x8d800, v173
	global_load_dwordx2 v[154:155], v131, s[14:15]
	v_mov_b32_e32 v140, v134
	v_mov_b32_e32 v141, v135
	s_nop 0
	v_permlane16_swap_b32_e32 v134, v140
	v_permlane16_swap_b32_e32 v135, v141
	v_add_f32_e32 v134, v134, v140
	v_add_f32_e32 v135, v135, v141
	v_mov_b32_e32 v140, v134
	v_mov_b32_e32 v141, v135
	s_nop 0
	v_permlane32_swap_b32_e32 v134, v140
	v_permlane32_swap_b32_e32 v135, v141
	v_add_f32_e32 v134, v134, v140
	v_add_f32_e32 v135, v135, v141
	s_and_saveexec_b64 s[10:11], s[4:5]
	global_atomic_add_f32 v175, v134, s[12:13] offset:384
	global_atomic_add_f32 v175, v135, s[12:13] offset:388
	s_or_b64 exec, exec, s[10:11]
	s_waitcnt vmcnt(33)
; template <int EPI>
; __device__ __forceinline__ void gemm_phase(const u16* __restrict__ A, const u16* __restrict__ Bt, const int K,
;                                            const int nN, char* shm, const EpiArgs& ea) {
;     ...
;               float mu = 0.f, rstd = 1.f;
;               if (EPI != EPI_FFN1) row_stats(ea.st_in, row, mu, rstd);
;               float rs = 0.f, rq = 0.f;
; #pragma unroll
;               for (int bj = 0; bj < 2; ++bj) {
;                 uint2 pk[2];
; #pragma unroll
;                 for (int n = 0; n < 2; ++n) {
;                   const int col = cb + bj * 128 + n * 16;
;                   f32x4 c = acc[ai][bj][m][n];
;                   float h[4];
;                   if (EPI == EPI_FFN1) {
;                     float4 rv = *(const float4*)(ea.res + (size_t)row * DM + col);
;                     h[0] = rv.x; h[1] = rv.y; h[2] = rv.z; h[3] = rv.w;
;                   } else {
;                     uint2 yv = *(const uint2*)((const char*)ea.yb + tl_off(row, col, DM >> 6));
;                     float4 gv = *(const float4*)(ea.lng + col);
;                     float4 bv = *(const float4*)(ea.lnb + col);
;                     h[0] = (bf_lo(yv.x) - mu) * rstd * gv.x + bv.x; h[1] = (bf_hi(yv.x) - mu) * rstd * gv.y + bv.y;
;                     h[2] = (bf_lo(yv.y) - mu) * rstd * gv.z + bv.z; h[3] = (bf_hi(yv.y) - mu) * rstd * gv.w + bv.w;
;                   }
;                   float y[4];
;                   if (EPI == EPI_OUT) {
;                     float4 bo = *(const float4*)(ea.bias + col);
;                     y[0] = ALPHA * h[0] + c[0] + bo.x; y[1] = ALPHA * h[1] + c[1] + bo.y;
;                     y[2] = ALPHA * h[2] + c[2] + bo.z; y[3] = ALPHA * h[3] + c[3] + bo.w;
;                   } else {
; #pragma unroll
;                     for (int j = 0; j < 4; ++j) y[j] = ALPHA * h[j] + 0.5f * c[j];
;                   }
;                   if (EPI == EPI_FFN2) {
;                     *(float4*)(ea.outf + (size_t)row * DM + col) = make_float4(y[0], y[1], y[2], y[3]);
;                   } else {
;                     pk[n] = make_uint2(pack2(y[0], y[1]), pack2(y[2], y[3]));
;                     float q0 = bf_lo(pk[n].x), q1 = bf_hi(pk[n].x), q2 = bf_lo(pk[n].y), q3 = bf_hi(pk[n].y);
;                     rs += (q0 + q1) + (q2 + q3);
;                     rq += (q0 * q0 + q1 * q1) + (q2 * q2 + q3 * q3);
;                   }
	v_pk_mul_f32 v[156:157], v[156:157], s[24:25] op_sel_hi:[1,0]
	v_add_u32_e32 v132, 0x84000, v128
	v_fma_f32 v164, -v156, v156, v157
	v_max_f32_e32 v164, 0, v164
	v_add_f32_e32 v164, 0x3727c5ac, v164
	v_rsq_f32_e32 v164, v164
	v_mov_b32_e32 v134, 0
	v_mov_b32_e32 v135, 0
	s_waitcnt vmcnt(32)
	v_lshlrev_b32_e32 v168, 16, v224
	v_and_b32_e32 v169, 0xffff0000, v224
	v_lshlrev_b32_e32 v170, 16, v225
	v_and_b32_e32 v171, 0xffff0000, v225
	v_pk_add_f32 v[168:169], v[168:169], v[156:157] op_sel_hi:[1,0] neg_lo:[0,1] neg_hi:[0,1]
	v_pk_add_f32 v[170:171], v[170:171], v[156:157] op_sel_hi:[1,0] neg_lo:[0,1] neg_hi:[0,1]
	v_pk_mul_f32 v[168:169], v[168:169], v[164:165] op_sel_hi:[1,0]
	v_pk_mul_f32 v[170:171], v[170:171], v[164:165] op_sel_hi:[1,0]
	v_pk_fma_f32 v[168:169], v[176:177], v[168:169], v[192:193]
	v_pk_fma_f32 v[170:171], v[178:179], v[170:171], v[194:195]
	v_pk_fma_f32 v[56:57], v[168:169], s[26:27], v[56:57] op_sel_hi:[1,0,1]
	v_pk_fma_f32 v[58:59], v[170:171], s[26:27], v[58:59] op_sel_hi:[1,0,1]
	v_pk_add_f32 v[56:57], v[208:209], v[56:57]
	v_pk_add_f32 v[58:59], v[210:211], v[58:59]
	v_cvt_pk_bf16_f32 v136, v56, v57
	v_cvt_pk_bf16_f32 v137, v58, v59
	v_lshlrev_b32_e32 v168, 16, v136
	v_and_b32_e32 v169, 0xffff0000, v136
	v_lshlrev_b32_e32 v170, 16, v137
	v_and_b32_e32 v171, 0xffff0000, v137
	v_add_f32_e32 v134, v134, v168
	v_fmac_f32_e32 v135, v168, v168
	v_add_f32_e32 v134, v134, v169
	v_fmac_f32_e32 v135, v169, v169
	v_add_f32_e32 v134, v134, v170
	v_fmac_f32_e32 v135, v170, v170
	v_add_f32_e32 v134, v134, v171
	v_fmac_f32_e32 v135, v171, v171
	s_waitcnt vmcnt(31)
	v_lshlrev_b32_e32 v168, 16, v226
	v_and_b32_e32 v169, 0xffff0000, v226
	v_lshlrev_b32_e32 v170, 16, v227
	v_and_b32_e32 v171, 0xffff0000, v227
	v_pk_add_f32 v[168:169], v[168:169], v[156:157] op_sel_hi:[1,0] neg_lo:[0,1] neg_hi:[0,1]
	v_pk_add_f32 v[170:171], v[170:171], v[156:157] op_sel_hi:[1,0] neg_lo:[0,1] neg_hi:[0,1]
	v_pk_mul_f32 v[168:169], v[168:169], v[164:165] op_sel_hi:[1,0]
	v_pk_mul_f32 v[170:171], v[170:171], v[164:165] op_sel_hi:[1,0]
	v_pk_fma_f32 v[168:169], v[180:181], v[168:169], v[196:197]
	v_pk_fma_f32 v[170:171], v[182:183], v[170:171], v[198:199]
	v_pk_fma_f32 v[60:61], v[168:169], s[26:27], v[60:61] op_sel_hi:[1,0,1]
	v_pk_fma_f32 v[62:63], v[170:171], s[26:27], v[62:63] op_sel_hi:[1,0,1]
	v_pk_add_f32 v[60:61], v[212:213], v[60:61]
	v_pk_add_f32 v[62:63], v[214:215], v[62:63]
	v_cvt_pk_bf16_f32 v138, v60, v61
	v_cvt_pk_bf16_f32 v139, v62, v63
	v_lshlrev_b32_e32 v168, 16, v138
	v_and_b32_e32 v169, 0xffff0000, v138
	v_lshlrev_b32_e32 v170, 16, v139
	v_and_b32_e32 v171, 0xffff0000, v139
	v_add_f32_e32 v134, v134, v168
	v_fmac_f32_e32 v135, v168, v168
	v_add_f32_e32 v134, v134, v169
	v_fmac_f32_e32 v135, v169, v169
	v_add_f32_e32 v134, v134, v170
	v_fmac_f32_e32 v135, v170, v170
	v_add_f32_e32 v134, v134, v171
	v_fmac_f32_e32 v135, v171, v171
	v_permlane16_swap_b32_e32 v136, v138
	v_permlane16_swap_b32_e32 v137, v139
	global_store_dwordx4 v132, v[136:139], s[14:15]
	s_waitcnt vmcnt(31)
	v_lshlrev_b32_e32 v168, 16, v228
	v_and_b32_e32 v169, 0xffff0000, v228
	v_lshlrev_b32_e32 v170, 16, v229
	v_and_b32_e32 v171, 0xffff0000, v229
	v_pk_add_f32 v[168:169], v[168:169], v[156:157] op_sel_hi:[1,0] neg_lo:[0,1] neg_hi:[0,1]
	v_pk_add_f32 v[170:171], v[170:171], v[156:157] op_sel_hi:[1,0] neg_lo:[0,1] neg_hi:[0,1]
	v_pk_mul_f32 v[168:169], v[168:169], v[164:165] op_sel_hi:[1,0]
	v_pk_mul_f32 v[170:171], v[170:171], v[164:165] op_sel_hi:[1,0]
	v_pk_fma_f32 v[168:169], v[184:185], v[168:169], v[200:201]
	v_pk_fma_f32 v[170:171], v[186:187], v[170:171], v[202:203]
	v_pk_fma_f32 v[52:53], v[168:169], s[26:27], v[52:53] op_sel_hi:[1,0,1]
	v_pk_fma_f32 v[54:55], v[170:171], s[26:27], v[54:55] op_sel_hi:[1,0,1]
	v_pk_add_f32 v[52:53], v[216:217], v[52:53]
	v_pk_add_f32 v[54:55], v[218:219], v[54:55]
	v_cvt_pk_bf16_f32 v136, v52, v53
	v_cvt_pk_bf16_f32 v137, v54, v55
	v_lshlrev_b32_e32 v168, 16, v136
	v_and_b32_e32 v169, 0xffff0000, v136
	v_lshlrev_b32_e32 v170, 16, v137
	v_and_b32_e32 v171, 0xffff0000, v137
	v_add_f32_e32 v134, v134, v168
	v_fmac_f32_e32 v135, v168, v168
	v_add_f32_e32 v134, v134, v169
	v_fmac_f32_e32 v135, v169, v169
	v_add_f32_e32 v134, v134, v170
	v_fmac_f32_e32 v135, v170, v170
	v_add_f32_e32 v134, v134, v171
	v_fmac_f32_e32 v135, v171, v171
	s_waitcnt vmcnt(30)
	v_lshlrev_b32_e32 v168, 16, v230
	v_and_b32_e32 v169, 0xffff0000, v230
	v_lshlrev_b32_e32 v170, 16, v231
	v_and_b32_e32 v171, 0xffff0000, v231
	v_pk_add_f32 v[168:169], v[168:169], v[156:157] op_sel_hi:[1,0] neg_lo:[0,1] neg_hi:[0,1]
	v_pk_add_f32 v[170:171], v[170:171], v[156:157] op_sel_hi:[1,0] neg_lo:[0,1] neg_hi:[0,1]
	v_pk_mul_f32 v[168:169], v[168:169], v[164:165] op_sel_hi:[1,0]
	v_pk_mul_f32 v[170:171], v[170:171], v[164:165] op_sel_hi:[1,0]
	v_pk_fma_f32 v[168:169], v[188:189], v[168:169], v[204:205]
	v_pk_fma_f32 v[170:171], v[190:191], v[170:171], v[206:207]
	v_pk_fma_f32 v[48:49], v[168:169], s[26:27], v[48:49] op_sel_hi:[1,0,1]
	v_pk_fma_f32 v[50:51], v[170:171], s[26:27], v[50:51] op_sel_hi:[1,0,1]
	v_pk_add_f32 v[48:49], v[220:221], v[48:49]
	v_pk_add_f32 v[50:51], v[222:223], v[50:51]
	v_cvt_pk_bf16_f32 v138, v48, v49
	v_cvt_pk_bf16_f32 v139, v50, v51
	v_lshlrev_b32_e32 v168, 16, v138
	v_and_b32_e32 v169, 0xffff0000, v138
	v_lshlrev_b32_e32 v170, 16, v139
	v_and_b32_e32 v171, 0xffff0000, v139
	v_add_f32_e32 v134, v134, v168
	v_fmac_f32_e32 v135, v168, v168
	v_add_f32_e32 v134, v134, v169
	v_fmac_f32_e32 v135, v169, v169
	v_add_f32_e32 v134, v134, v170
	v_fmac_f32_e32 v135, v170, v170
	v_add_f32_e32 v134, v134, v171
	v_fmac_f32_e32 v135, v171, v171
	v_permlane16_swap_b32_e32 v136, v138
	v_permlane16_swap_b32_e32 v137, v139
	v_add_u32_e32 v133, 0x8000, v132
	global_store_dwordx4 v133, v[136:139], s[14:15]
	v_mov_b32_e32 v140, v134
	v_mov_b32_e32 v141, v135
	s_nop 0
	v_permlane16_swap_b32_e32 v134, v140
	v_permlane16_swap_b32_e32 v135, v141
	v_add_f32_e32 v134, v134, v140
	v_add_f32_e32 v135, v135, v141
	v_mov_b32_e32 v140, v134
	v_mov_b32_e32 v141, v135
	s_nop 0
	v_permlane32_swap_b32_e32 v134, v140
	v_permlane32_swap_b32_e32 v135, v141
	v_add_f32_e32 v134, v134, v140
	v_add_f32_e32 v135, v135, v141
	s_and_saveexec_b64 s[10:11], s[4:5]
	global_atomic_add_f32 v175, v134, s[12:13] offset:1024
	global_atomic_add_f32 v175, v135, s[12:13] offset:1028
	s_or_b64 exec, exec, s[10:11]
	s_waitcnt vmcnt(28)
; template <int EPI>
; __device__ __forceinline__ void gemm_phase(const u16* __restrict__ A, const u16* __restrict__ Bt, const int K,
;                                            const int nN, char* shm, const EpiArgs& ea) {
;     ...
;               float mu = 0.f, rstd = 1.f;
;               if (EPI != EPI_FFN1) row_stats(ea.st_in, row, mu, rstd);
;               float rs = 0.f, rq = 0.f;
; #pragma unroll
;               for (int bj = 0; bj < 2; ++bj) {
;                 uint2 pk[2];
; #pragma unroll
;                 for (int n = 0; n < 2; ++n) {
;                   const int col = cb + bj * 128 + n * 16;
;                   f32x4 c = acc[ai][bj][m][n];
;                   float h[4];
;                   if (EPI == EPI_FFN1) {
;                     float4 rv = *(const float4*)(ea.res + (size_t)row * DM + col);
;                     h[0] = rv.x; h[1] = rv.y; h[2] = rv.z; h[3] = rv.w;
;                   } else {
;                     uint2 yv = *(const uint2*)((const char*)ea.yb + tl_off(row, col, DM >> 6));
;                     float4 gv = *(const float4*)(ea.lng + col);
;                     float4 bv = *(const float4*)(ea.lnb + col);
;                     h[0] = (bf_lo(yv.x) - mu) * rstd * gv.x + bv.x; h[1] = (bf_hi(yv.x) - mu) * rstd * gv.y + bv.y;
;                     h[2] = (bf_lo(yv.y) - mu) * rstd * gv.z + bv.z; h[3] = (bf_hi(yv.y) - mu) * rstd * gv.w + bv.w;
;                   }
;                   float y[4];
;                   if (EPI == EPI_OUT) {
;                     float4 bo = *(const float4*)(ea.bias + col);
;                     y[0] = ALPHA * h[0] + c[0] + bo.x; y[1] = ALPHA * h[1] + c[1] + bo.y;
;                     y[2] = ALPHA * h[2] + c[2] + bo.z; y[3] = ALPHA * h[3] + c[3] + bo.w;
;                   } else {
; #pragma unroll
;                     for (int j = 0; j < 4; ++j) y[j] = ALPHA * h[j] + 0.5f * c[j];
;                   }
;                   if (EPI == EPI_FFN2) {
;                     *(float4*)(ea.outf + (size_t)row * DM + col) = make_float4(y[0], y[1], y[2], y[3]);
;                   } else {
;                     pk[n] = make_uint2(pack2(y[0], y[1]), pack2(y[2], y[3]));
;                     float q0 = bf_lo(pk[n].x), q1 = bf_hi(pk[n].x), q2 = bf_lo(pk[n].y), q3 = bf_hi(pk[n].y);
;                     rs += (q0 + q1) + (q2 + q3);
;                     rq += (q0 * q0 + q1 * q1) + (q2 * q2 + q3 * q3);
;                   }
	v_pk_mul_f32 v[158:159], v[158:159], s[24:25] op_sel_hi:[1,0]
	v_add_u32_e32 v132, 0x84800, v128
	v_fma_f32 v166, -v158, v158, v159
	v_max_f32_e32 v166, 0, v166
	v_add_f32_e32 v166, 0x3727c5ac, v166
	v_rsq_f32_e32 v166, v166
	v_mov_b32_e32 v134, 0
	v_mov_b32_e32 v135, 0
	s_waitcnt vmcnt(27)
	v_lshlrev_b32_e32 v168, 16, v232
	v_and_b32_e32 v169, 0xffff0000, v232
	v_lshlrev_b32_e32 v170, 16, v233
	v_and_b32_e32 v171, 0xffff0000, v233
	v_pk_add_f32 v[168:169], v[168:169], v[158:159] op_sel_hi:[1,0] neg_lo:[0,1] neg_hi:[0,1]
	v_pk_add_f32 v[170:171], v[170:171], v[158:159] op_sel_hi:[1,0] neg_lo:[0,1] neg_hi:[0,1]
	v_pk_mul_f32 v[168:169], v[168:169], v[166:167] op_sel_hi:[1,0]
	v_pk_mul_f32 v[170:171], v[170:171], v[166:167] op_sel_hi:[1,0]
	v_pk_fma_f32 v[168:169], v[176:177], v[168:169], v[192:193]
	v_pk_fma_f32 v[170:171], v[178:179], v[170:171], v[194:195]
	v_pk_fma_f32 v[40:41], v[168:169], s[26:27], v[40:41] op_sel_hi:[1,0,1]
	v_pk_fma_f32 v[42:43], v[170:171], s[26:27], v[42:43] op_sel_hi:[1,0,1]
	v_pk_add_f32 v[40:41], v[208:209], v[40:41]
	v_pk_add_f32 v[42:43], v[210:211], v[42:43]
	v_cvt_pk_bf16_f32 v136, v40, v41
	v_cvt_pk_bf16_f32 v137, v42, v43
	v_lshlrev_b32_e32 v168, 16, v136
	v_and_b32_e32 v169, 0xffff0000, v136
	v_lshlrev_b32_e32 v170, 16, v137
	v_and_b32_e32 v171, 0xffff0000, v137
	v_add_f32_e32 v134, v134, v168
	v_fmac_f32_e32 v135, v168, v168
	v_add_f32_e32 v134, v134, v169
	v_fmac_f32_e32 v135, v169, v169
	v_add_f32_e32 v134, v134, v170
	v_fmac_f32_e32 v135, v170, v170
	v_add_f32_e32 v134, v134, v171
	v_fmac_f32_e32 v135, v171, v171
	s_waitcnt vmcnt(26)
	v_lshlrev_b32_e32 v168, 16, v234
	v_and_b32_e32 v169, 0xffff0000, v234
	v_lshlrev_b32_e32 v170, 16, v235
	v_and_b32_e32 v171, 0xffff0000, v235
	v_pk_add_f32 v[168:169], v[168:169], v[158:159] op_sel_hi:[1,0] neg_lo:[0,1] neg_hi:[0,1]
	v_pk_add_f32 v[170:171], v[170:171], v[158:159] op_sel_hi:[1,0] neg_lo:[0,1] neg_hi:[0,1]
	v_pk_mul_f32 v[168:169], v[168:169], v[166:167] op_sel_hi:[1,0]
	v_pk_mul_f32 v[170:171], v[170:171], v[166:167] op_sel_hi:[1,0]
	v_pk_fma_f32 v[168:169], v[180:181], v[168:169], v[196:197]
	v_pk_fma_f32 v[170:171], v[182:183], v[170:171], v[198:199]
	v_pk_fma_f32 v[44:45], v[168:169], s[26:27], v[44:45] op_sel_hi:[1,0,1]
	v_pk_fma_f32 v[46:47], v[170:171], s[26:27], v[46:47] op_sel_hi:[1,0,1]
	v_pk_add_f32 v[44:45], v[212:213], v[44:45]
	v_pk_add_f32 v[46:47], v[214:215], v[46:47]
	v_cvt_pk_bf16_f32 v138, v44, v45
	v_cvt_pk_bf16_f32 v139, v46, v47
	v_lshlrev_b32_e32 v168, 16, v138
	v_and_b32_e32 v169, 0xffff0000, v138
	v_lshlrev_b32_e32 v170, 16, v139
	v_and_b32_e32 v171, 0xffff0000, v139
	v_add_f32_e32 v134, v134, v168
	v_fmac_f32_e32 v135, v168, v168
	v_add_f32_e32 v134, v134, v169
	v_fmac_f32_e32 v135, v169, v169
	v_add_f32_e32 v134, v134, v170
	v_fmac_f32_e32 v135, v170, v170
	v_add_f32_e32 v134, v134, v171
	v_fmac_f32_e32 v135, v171, v171
	v_permlane16_swap_b32_e32 v136, v138
	v_permlane16_swap_b32_e32 v137, v139
	global_store_dwordx4 v132, v[136:139], s[14:15]
	s_waitcnt vmcnt(26)
	v_lshlrev_b32_e32 v168, 16, v236
	v_and_b32_e32 v169, 0xffff0000, v236
	v_lshlrev_b32_e32 v170, 16, v237
	v_and_b32_e32 v171, 0xffff0000, v237
	v_pk_add_f32 v[168:169], v[168:169], v[158:159] op_sel_hi:[1,0] neg_lo:[0,1] neg_hi:[0,1]
	v_pk_add_f32 v[170:171], v[170:171], v[158:159] op_sel_hi:[1,0] neg_lo:[0,1] neg_hi:[0,1]
	v_pk_mul_f32 v[168:169], v[168:169], v[166:167] op_sel_hi:[1,0]
	v_pk_mul_f32 v[170:171], v[170:171], v[166:167] op_sel_hi:[1,0]
	v_pk_fma_f32 v[168:169], v[184:185], v[168:169], v[200:201]
	v_pk_fma_f32 v[170:171], v[186:187], v[170:171], v[202:203]
	v_pk_fma_f32 v[36:37], v[168:169], s[26:27], v[36:37] op_sel_hi:[1,0,1]
	v_pk_fma_f32 v[38:39], v[170:171], s[26:27], v[38:39] op_sel_hi:[1,0,1]
	v_pk_add_f32 v[36:37], v[216:217], v[36:37]
	v_pk_add_f32 v[38:39], v[218:219], v[38:39]
	v_cvt_pk_bf16_f32 v136, v36, v37
	v_cvt_pk_bf16_f32 v137, v38, v39
	v_lshlrev_b32_e32 v168, 16, v136
	v_and_b32_e32 v169, 0xffff0000, v136
	v_lshlrev_b32_e32 v170, 16, v137
	v_and_b32_e32 v171, 0xffff0000, v137
	v_add_f32_e32 v134, v134, v168
	v_fmac_f32_e32 v135, v168, v168
	v_add_f32_e32 v134, v134, v169
	v_fmac_f32_e32 v135, v169, v169
	v_add_f32_e32 v134, v134, v170
	v_fmac_f32_e32 v135, v170, v170
	v_add_f32_e32 v134, v134, v171
	v_fmac_f32_e32 v135, v171, v171
	s_waitcnt vmcnt(25)
	v_lshlrev_b32_e32 v168, 16, v238
	v_and_b32_e32 v169, 0xffff0000, v238
	v_lshlrev_b32_e32 v170, 16, v239
	v_and_b32_e32 v171, 0xffff0000, v239
	v_pk_add_f32 v[168:169], v[168:169], v[158:159] op_sel_hi:[1,0] neg_lo:[0,1] neg_hi:[0,1]
	v_pk_add_f32 v[170:171], v[170:171], v[158:159] op_sel_hi:[1,0] neg_lo:[0,1] neg_hi:[0,1]
	v_pk_mul_f32 v[168:169], v[168:169], v[166:167] op_sel_hi:[1,0]
	v_pk_mul_f32 v[170:171], v[170:171], v[166:167] op_sel_hi:[1,0]
	v_pk_fma_f32 v[168:169], v[188:189], v[168:169], v[204:205]
	v_pk_fma_f32 v[170:171], v[190:191], v[170:171], v[206:207]
	v_pk_fma_f32 v[32:33], v[168:169], s[26:27], v[32:33] op_sel_hi:[1,0,1]
	v_pk_fma_f32 v[34:35], v[170:171], s[26:27], v[34:35] op_sel_hi:[1,0,1]
	v_pk_add_f32 v[32:33], v[220:221], v[32:33]
	v_pk_add_f32 v[34:35], v[222:223], v[34:35]
	v_cvt_pk_bf16_f32 v138, v32, v33
	v_cvt_pk_bf16_f32 v139, v34, v35
	v_lshlrev_b32_e32 v168, 16, v138
	v_and_b32_e32 v169, 0xffff0000, v138
	v_lshlrev_b32_e32 v170, 16, v139
	v_and_b32_e32 v171, 0xffff0000, v139
	v_add_f32_e32 v134, v134, v168
	v_fmac_f32_e32 v135, v168, v168
	v_add_f32_e32 v134, v134, v169
	v_fmac_f32_e32 v135, v169, v169
	v_add_f32_e32 v134, v134, v170
	v_fmac_f32_e32 v135, v170, v170
	v_add_f32_e32 v134, v134, v171
	v_fmac_f32_e32 v135, v171, v171
	v_permlane16_swap_b32_e32 v136, v138
	v_permlane16_swap_b32_e32 v137, v139
	v_add_u32_e32 v133, 0x8000, v132
	global_store_dwordx4 v133, v[136:139], s[14:15]
	v_mov_b32_e32 v140, v134
	v_mov_b32_e32 v141, v135
	s_nop 0
	v_permlane16_swap_b32_e32 v134, v140
	v_permlane16_swap_b32_e32 v135, v141
	v_add_f32_e32 v134, v134, v140
	v_add_f32_e32 v135, v135, v141
	v_mov_b32_e32 v140, v134
	v_mov_b32_e32 v141, v135
	s_nop 0
	v_permlane32_swap_b32_e32 v134, v140
	v_permlane32_swap_b32_e32 v135, v141
	v_add_f32_e32 v134, v134, v140
	v_add_f32_e32 v135, v135, v141
	s_and_saveexec_b64 s[10:11], s[4:5]
	global_atomic_add_f32 v175, v134, s[12:13] offset:1152
	global_atomic_add_f32 v175, v135, s[12:13] offset:1156
	s_or_b64 exec, exec, s[10:11]
	s_waitcnt vmcnt(23)
; template <int EPI>
; __device__ __forceinline__ void gemm_phase(const u16* __restrict__ A, const u16* __restrict__ Bt, const int K,
;                                            const int nN, char* shm, const EpiArgs& ea) {
;     ...
;               float mu = 0.f, rstd = 1.f;
;               if (EPI != EPI_FFN1) row_stats(ea.st_in, row, mu, rstd);
;               float rs = 0.f, rq = 0.f;
; #pragma unroll
;               for (int bj = 0; bj < 2; ++bj) {
;                 uint2 pk[2];
; #pragma unroll
;                 for (int n = 0; n < 2; ++n) {
;                   const int col = cb + bj * 128 + n * 16;
;                   f32x4 c = acc[ai][bj][m][n];
;                   float h[4];
;                   if (EPI == EPI_FFN1) {
;                     float4 rv = *(const float4*)(ea.res + (size_t)row * DM + col);
;                     h[0] = rv.x; h[1] = rv.y; h[2] = rv.z; h[3] = rv.w;
;                   } else {
;                     uint2 yv = *(const uint2*)((const char*)ea.yb + tl_off(row, col, DM >> 6));
;                     float4 gv = *(const float4*)(ea.lng + col);
;                     float4 bv = *(const float4*)(ea.lnb + col);
;                     h[0] = (bf_lo(yv.x) - mu) * rstd * gv.x + bv.x; h[1] = (bf_hi(yv.x) - mu) * rstd * gv.y + bv.y;
;                     h[2] = (bf_lo(yv.y) - mu) * rstd * gv.z + bv.z; h[3] = (bf_hi(yv.y) - mu) * rstd * gv.w + bv.w;
;                   }
;                   float y[4];
;                   if (EPI == EPI_OUT) {
;                     float4 bo = *(const float4*)(ea.bias + col);
;                     y[0] = ALPHA * h[0] + c[0] + bo.x; y[1] = ALPHA * h[1] + c[1] + bo.y;
;                     y[2] = ALPHA * h[2] + c[2] + bo.z; y[3] = ALPHA * h[3] + c[3] + bo.w;
;                   } else {
; #pragma unroll
;                     for (int j = 0; j < 4; ++j) y[j] = ALPHA * h[j] + 0.5f * c[j];
;                   }
;                   if (EPI == EPI_FFN2) {
;                     *(float4*)(ea.outf + (size_t)row * DM + col) = make_float4(y[0], y[1], y[2], y[3]);
;                   } else {
;                     pk[n] = make_uint2(pack2(y[0], y[1]), pack2(y[2], y[3]));
;                     float q0 = bf_lo(pk[n].x), q1 = bf_hi(pk[n].x), q2 = bf_lo(pk[n].y), q3 = bf_hi(pk[n].y);
;                     rs += (q0 + q1) + (q2 + q3);
;                     rq += (q0 * q0 + q1 * q1) + (q2 * q2 + q3 * q3);
;                   }
	v_pk_mul_f32 v[160:161], v[160:161], s[24:25] op_sel_hi:[1,0]
	v_add_u32_e32 v132, 0x85000, v128
	v_fma_f32 v164, -v160, v160, v161
	v_max_f32_e32 v164, 0, v164
	v_add_f32_e32 v164, 0x3727c5ac, v164
	v_rsq_f32_e32 v164, v164
	v_mov_b32_e32 v134, 0
	v_mov_b32_e32 v135, 0
	s_waitcnt vmcnt(22)
	v_lshlrev_b32_e32 v168, 16, v240
	v_and_b32_e32 v169, 0xffff0000, v240
	v_lshlrev_b32_e32 v170, 16, v241
	v_and_b32_e32 v171, 0xffff0000, v241
	v_pk_add_f32 v[168:169], v[168:169], v[160:161] op_sel_hi:[1,0] neg_lo:[0,1] neg_hi:[0,1]
	v_pk_add_f32 v[170:171], v[170:171], v[160:161] op_sel_hi:[1,0] neg_lo:[0,1] neg_hi:[0,1]
	v_pk_mul_f32 v[168:169], v[168:169], v[164:165] op_sel_hi:[1,0]
	v_pk_mul_f32 v[170:171], v[170:171], v[164:165] op_sel_hi:[1,0]
	v_pk_fma_f32 v[168:169], v[176:177], v[168:169], v[192:193]
	v_pk_fma_f32 v[170:171], v[178:179], v[170:171], v[194:195]
	v_pk_fma_f32 v[24:25], v[168:169], s[26:27], v[24:25] op_sel_hi:[1,0,1]
	v_pk_fma_f32 v[26:27], v[170:171], s[26:27], v[26:27] op_sel_hi:[1,0,1]
	v_pk_add_f32 v[24:25], v[208:209], v[24:25]
	v_pk_add_f32 v[26:27], v[210:211], v[26:27]
	v_cvt_pk_bf16_f32 v136, v24, v25
	v_cvt_pk_bf16_f32 v137, v26, v27
	v_lshlrev_b32_e32 v168, 16, v136
	v_and_b32_e32 v169, 0xffff0000, v136
	v_lshlrev_b32_e32 v170, 16, v137
	v_and_b32_e32 v171, 0xffff0000, v137
	v_add_f32_e32 v134, v134, v168
	v_fmac_f32_e32 v135, v168, v168
	v_add_f32_e32 v134, v134, v169
	v_fmac_f32_e32 v135, v169, v169
	v_add_f32_e32 v134, v134, v170
	v_fmac_f32_e32 v135, v170, v170
	v_add_f32_e32 v134, v134, v171
	v_fmac_f32_e32 v135, v171, v171
	s_waitcnt vmcnt(21)
	v_lshlrev_b32_e32 v168, 16, v242
	v_and_b32_e32 v169, 0xffff0000, v242
	v_lshlrev_b32_e32 v170, 16, v243
	v_and_b32_e32 v171, 0xffff0000, v243
	v_pk_add_f32 v[168:169], v[168:169], v[160:161] op_sel_hi:[1,0] neg_lo:[0,1] neg_hi:[0,1]
	v_pk_add_f32 v[170:171], v[170:171], v[160:161] op_sel_hi:[1,0] neg_lo:[0,1] neg_hi:[0,1]
	v_pk_mul_f32 v[168:169], v[168:169], v[164:165] op_sel_hi:[1,0]
	v_pk_mul_f32 v[170:171], v[170:171], v[164:165] op_sel_hi:[1,0]
	v_pk_fma_f32 v[168:169], v[180:181], v[168:169], v[196:197]
	v_pk_fma_f32 v[170:171], v[182:183], v[170:171], v[198:199]
	v_pk_fma_f32 v[28:29], v[168:169], s[26:27], v[28:29] op_sel_hi:[1,0,1]
	v_pk_fma_f32 v[30:31], v[170:171], s[26:27], v[30:31] op_sel_hi:[1,0,1]
	v_pk_add_f32 v[28:29], v[212:213], v[28:29]
	v_pk_add_f32 v[30:31], v[214:215], v[30:31]
	v_cvt_pk_bf16_f32 v138, v28, v29
	v_cvt_pk_bf16_f32 v139, v30, v31
	v_lshlrev_b32_e32 v168, 16, v138
	v_and_b32_e32 v169, 0xffff0000, v138
	v_lshlrev_b32_e32 v170, 16, v139
	v_and_b32_e32 v171, 0xffff0000, v139
	v_add_f32_e32 v134, v134, v168
	v_fmac_f32_e32 v135, v168, v168
	v_add_f32_e32 v134, v134, v169
	v_fmac_f32_e32 v135, v169, v169
	v_add_f32_e32 v134, v134, v170
	v_fmac_f32_e32 v135, v170, v170
	v_add_f32_e32 v134, v134, v171
	v_fmac_f32_e32 v135, v171, v171
	v_permlane16_swap_b32_e32 v136, v138
	v_permlane16_swap_b32_e32 v137, v139
	global_store_dwordx4 v132, v[136:139], s[14:15]
	s_waitcnt vmcnt(21)
	v_lshlrev_b32_e32 v168, 16, v246
	v_and_b32_e32 v169, 0xffff0000, v246
	v_lshlrev_b32_e32 v170, 16, v247
	v_and_b32_e32 v171, 0xffff0000, v247
	v_pk_add_f32 v[168:169], v[168:169], v[160:161] op_sel_hi:[1,0] neg_lo:[0,1] neg_hi:[0,1]
	v_pk_add_f32 v[170:171], v[170:171], v[160:161] op_sel_hi:[1,0] neg_lo:[0,1] neg_hi:[0,1]
	v_pk_mul_f32 v[168:169], v[168:169], v[164:165] op_sel_hi:[1,0]
	v_pk_mul_f32 v[170:171], v[170:171], v[164:165] op_sel_hi:[1,0]
	v_pk_fma_f32 v[168:169], v[184:185], v[168:169], v[200:201]
	v_pk_fma_f32 v[170:171], v[186:187], v[170:171], v[202:203]
	v_pk_fma_f32 v[20:21], v[168:169], s[26:27], v[20:21] op_sel_hi:[1,0,1]
	v_pk_fma_f32 v[22:23], v[170:171], s[26:27], v[22:23] op_sel_hi:[1,0,1]
	v_pk_add_f32 v[20:21], v[216:217], v[20:21]
	v_pk_add_f32 v[22:23], v[218:219], v[22:23]
	v_cvt_pk_bf16_f32 v136, v20, v21
	v_cvt_pk_bf16_f32 v137, v22, v23
	v_lshlrev_b32_e32 v168, 16, v136
	v_and_b32_e32 v169, 0xffff0000, v136
	v_lshlrev_b32_e32 v170, 16, v137
	v_and_b32_e32 v171, 0xffff0000, v137
	v_add_f32_e32 v134, v134, v168
	v_fmac_f32_e32 v135, v168, v168
	v_add_f32_e32 v134, v134, v169
	v_fmac_f32_e32 v135, v169, v169
	v_add_f32_e32 v134, v134, v170
	v_fmac_f32_e32 v135, v170, v170
	v_add_f32_e32 v134, v134, v171
	v_fmac_f32_e32 v135, v171, v171
	s_waitcnt vmcnt(20)
	v_lshlrev_b32_e32 v168, 16, v248
	v_and_b32_e32 v169, 0xffff0000, v248
	v_lshlrev_b32_e32 v170, 16, v249
	v_and_b32_e32 v171, 0xffff0000, v249
	v_pk_add_f32 v[168:169], v[168:169], v[160:161] op_sel_hi:[1,0] neg_lo:[0,1] neg_hi:[0,1]
	v_pk_add_f32 v[170:171], v[170:171], v[160:161] op_sel_hi:[1,0] neg_lo:[0,1] neg_hi:[0,1]
	v_pk_mul_f32 v[168:169], v[168:169], v[164:165] op_sel_hi:[1,0]
	v_pk_mul_f32 v[170:171], v[170:171], v[164:165] op_sel_hi:[1,0]
	v_pk_fma_f32 v[168:169], v[188:189], v[168:169], v[204:205]
	v_pk_fma_f32 v[170:171], v[190:191], v[170:171], v[206:207]
	v_pk_fma_f32 v[16:17], v[168:169], s[26:27], v[16:17] op_sel_hi:[1,0,1]
	v_pk_fma_f32 v[18:19], v[170:171], s[26:27], v[18:19] op_sel_hi:[1,0,1]
	v_pk_add_f32 v[16:17], v[220:221], v[16:17]
	v_pk_add_f32 v[18:19], v[222:223], v[18:19]
	v_cvt_pk_bf16_f32 v138, v16, v17
	v_cvt_pk_bf16_f32 v139, v18, v19
	v_lshlrev_b32_e32 v168, 16, v138
	v_and_b32_e32 v169, 0xffff0000, v138
	v_lshlrev_b32_e32 v170, 16, v139
	v_and_b32_e32 v171, 0xffff0000, v139
	v_add_f32_e32 v134, v134, v168
	v_fmac_f32_e32 v135, v168, v168
	v_add_f32_e32 v134, v134, v169
	v_fmac_f32_e32 v135, v169, v169
	v_add_f32_e32 v134, v134, v170
	v_fmac_f32_e32 v135, v170, v170
	v_add_f32_e32 v134, v134, v171
	v_fmac_f32_e32 v135, v171, v171
	v_permlane16_swap_b32_e32 v136, v138
	v_permlane16_swap_b32_e32 v137, v139
	v_add_u32_e32 v133, 0x8000, v132
	global_store_dwordx4 v133, v[136:139], s[14:15]
	v_mov_b32_e32 v140, v134
	v_mov_b32_e32 v141, v135
	s_nop 0
	v_permlane16_swap_b32_e32 v134, v140
	v_permlane16_swap_b32_e32 v135, v141
	v_add_f32_e32 v134, v134, v140
	v_add_f32_e32 v135, v135, v141
	v_mov_b32_e32 v140, v134
	v_mov_b32_e32 v141, v135
	s_nop 0
	v_permlane32_swap_b32_e32 v134, v140
	v_permlane32_swap_b32_e32 v135, v141
	v_add_f32_e32 v134, v134, v140
	v_add_f32_e32 v135, v135, v141
	s_and_saveexec_b64 s[10:11], s[4:5]
	global_atomic_add_f32 v175, v134, s[12:13] offset:1280
	global_atomic_add_f32 v175, v135, s[12:13] offset:1284
	s_or_b64 exec, exec, s[10:11]
	s_waitcnt vmcnt(18)
; template <int EPI>
; __device__ __forceinline__ void gemm_phase(const u16* __restrict__ A, const u16* __restrict__ Bt, const int K,
;                                            const int nN, char* shm, const EpiArgs& ea) {
;     ...
;               float mu = 0.f, rstd = 1.f;
;               if (EPI != EPI_FFN1) row_stats(ea.st_in, row, mu, rstd);
;               float rs = 0.f, rq = 0.f;
; #pragma unroll
;               for (int bj = 0; bj < 2; ++bj) {
;                 uint2 pk[2];
; #pragma unroll
;                 for (int n = 0; n < 2; ++n) {
;                   const int col = cb + bj * 128 + n * 16;
;                   f32x4 c = acc[ai][bj][m][n];
;                   float h[4];
;                   if (EPI == EPI_FFN1) {
;                     float4 rv = *(const float4*)(ea.res + (size_t)row * DM + col);
;                     h[0] = rv.x; h[1] = rv.y; h[2] = rv.z; h[3] = rv.w;
;                   } else {
;                     uint2 yv = *(const uint2*)((const char*)ea.yb + tl_off(row, col, DM >> 6));
;                     float4 gv = *(const float4*)(ea.lng + col);
;                     float4 bv = *(const float4*)(ea.lnb + col);
;                     h[0] = (bf_lo(yv.x) - mu) * rstd * gv.x + bv.x; h[1] = (bf_hi(yv.x) - mu) * rstd * gv.y + bv.y;
;                     h[2] = (bf_lo(yv.y) - mu) * rstd * gv.z + bv.z; h[3] = (bf_hi(yv.y) - mu) * rstd * gv.w + bv.w;
;                   }
;                   float y[4];
;                   if (EPI == EPI_OUT) {
;                     float4 bo = *(const float4*)(ea.bias + col);
;                     y[0] = ALPHA * h[0] + c[0] + bo.x; y[1] = ALPHA * h[1] + c[1] + bo.y;
;                     y[2] = ALPHA * h[2] + c[2] + bo.z; y[3] = ALPHA * h[3] + c[3] + bo.w;
;                   } else {
; #pragma unroll
;                     for (int j = 0; j < 4; ++j) y[j] = ALPHA * h[j] + 0.5f * c[j];
;                   }
;                   if (EPI == EPI_FFN2) {
;                     *(float4*)(ea.outf + (size_t)row * DM + col) = make_float4(y[0], y[1], y[2], y[3]);
;                   } else {
;                     pk[n] = make_uint2(pack2(y[0], y[1]), pack2(y[2], y[3]));
;                     float q0 = bf_lo(pk[n].x), q1 = bf_hi(pk[n].x), q2 = bf_lo(pk[n].y), q3 = bf_hi(pk[n].y);
;                     rs += (q0 + q1) + (q2 + q3);
;                     rq += (q0 * q0 + q1 * q1) + (q2 * q2 + q3 * q3);
;                   }
	v_pk_mul_f32 v[162:163], v[162:163], s[24:25] op_sel_hi:[1,0]
	v_add_u32_e32 v132, 0x85800, v128
	v_fma_f32 v166, -v162, v162, v163
	v_max_f32_e32 v166, 0, v166
	v_add_f32_e32 v166, 0x3727c5ac, v166
	v_rsq_f32_e32 v166, v166
	v_mov_b32_e32 v134, 0
	v_mov_b32_e32 v135, 0
	s_waitcnt vmcnt(17)
	v_lshlrev_b32_e32 v168, 16, v250
	v_and_b32_e32 v169, 0xffff0000, v250
	v_lshlrev_b32_e32 v170, 16, v251
	v_and_b32_e32 v171, 0xffff0000, v251
	v_pk_add_f32 v[168:169], v[168:169], v[162:163] op_sel_hi:[1,0] neg_lo:[0,1] neg_hi:[0,1]
	v_pk_add_f32 v[170:171], v[170:171], v[162:163] op_sel_hi:[1,0] neg_lo:[0,1] neg_hi:[0,1]
	v_pk_mul_f32 v[168:169], v[168:169], v[166:167] op_sel_hi:[1,0]
	v_pk_mul_f32 v[170:171], v[170:171], v[166:167] op_sel_hi:[1,0]
	v_pk_fma_f32 v[168:169], v[176:177], v[168:169], v[192:193]
	v_pk_fma_f32 v[170:171], v[178:179], v[170:171], v[194:195]
	v_pk_fma_f32 v[8:9], v[168:169], s[26:27], v[8:9] op_sel_hi:[1,0,1]
	v_pk_fma_f32 v[10:11], v[170:171], s[26:27], v[10:11] op_sel_hi:[1,0,1]
	v_pk_add_f32 v[8:9], v[208:209], v[8:9]
	v_pk_add_f32 v[10:11], v[210:211], v[10:11]
	v_cvt_pk_bf16_f32 v136, v8, v9
	v_cvt_pk_bf16_f32 v137, v10, v11
	v_lshlrev_b32_e32 v168, 16, v136
	v_and_b32_e32 v169, 0xffff0000, v136
	v_lshlrev_b32_e32 v170, 16, v137
	v_and_b32_e32 v171, 0xffff0000, v137
	v_add_f32_e32 v134, v134, v168
	v_fmac_f32_e32 v135, v168, v168
	v_add_f32_e32 v134, v134, v169
	v_fmac_f32_e32 v135, v169, v169
	v_add_f32_e32 v134, v134, v170
	v_fmac_f32_e32 v135, v170, v170
	v_add_f32_e32 v134, v134, v171
	v_fmac_f32_e32 v135, v171, v171
	s_waitcnt vmcnt(16)
	v_lshlrev_b32_e32 v168, 16, v252
	v_and_b32_e32 v169, 0xffff0000, v252
	v_lshlrev_b32_e32 v170, 16, v253
	v_and_b32_e32 v171, 0xffff0000, v253
	v_pk_add_f32 v[168:169], v[168:169], v[162:163] op_sel_hi:[1,0] neg_lo:[0,1] neg_hi:[0,1]
	v_pk_add_f32 v[170:171], v[170:171], v[162:163] op_sel_hi:[1,0] neg_lo:[0,1] neg_hi:[0,1]
	v_pk_mul_f32 v[168:169], v[168:169], v[166:167] op_sel_hi:[1,0]
	v_pk_mul_f32 v[170:171], v[170:171], v[166:167] op_sel_hi:[1,0]
	v_pk_fma_f32 v[168:169], v[180:181], v[168:169], v[196:197]
	v_pk_fma_f32 v[170:171], v[182:183], v[170:171], v[198:199]
	v_pk_fma_f32 v[12:13], v[168:169], s[26:27], v[12:13] op_sel_hi:[1,0,1]
	v_pk_fma_f32 v[14:15], v[170:171], s[26:27], v[14:15] op_sel_hi:[1,0,1]
	v_pk_add_f32 v[12:13], v[212:213], v[12:13]
	v_pk_add_f32 v[14:15], v[214:215], v[14:15]
	v_cvt_pk_bf16_f32 v138, v12, v13
	v_cvt_pk_bf16_f32 v139, v14, v15
	v_lshlrev_b32_e32 v168, 16, v138
	v_and_b32_e32 v169, 0xffff0000, v138
	v_lshlrev_b32_e32 v170, 16, v139
	v_and_b32_e32 v171, 0xffff0000, v139
	v_add_f32_e32 v134, v134, v168
	v_fmac_f32_e32 v135, v168, v168
	v_add_f32_e32 v134, v134, v169
	v_fmac_f32_e32 v135, v169, v169
	v_add_f32_e32 v134, v134, v170
	v_fmac_f32_e32 v135, v170, v170
	v_add_f32_e32 v134, v134, v171
	v_fmac_f32_e32 v135, v171, v171
	v_permlane16_swap_b32_e32 v136, v138
	v_permlane16_swap_b32_e32 v137, v139
	global_store_dwordx4 v132, v[136:139], s[14:15]
	s_waitcnt vmcnt(16)
	v_lshlrev_b32_e32 v168, 16, v254
	v_and_b32_e32 v169, 0xffff0000, v254
	v_lshlrev_b32_e32 v170, 16, v255
	v_and_b32_e32 v171, 0xffff0000, v255
	v_pk_add_f32 v[168:169], v[168:169], v[162:163] op_sel_hi:[1,0] neg_lo:[0,1] neg_hi:[0,1]
	v_pk_add_f32 v[170:171], v[170:171], v[162:163] op_sel_hi:[1,0] neg_lo:[0,1] neg_hi:[0,1]
	v_pk_mul_f32 v[168:169], v[168:169], v[166:167] op_sel_hi:[1,0]
	v_pk_mul_f32 v[170:171], v[170:171], v[166:167] op_sel_hi:[1,0]
	v_pk_fma_f32 v[168:169], v[184:185], v[168:169], v[200:201]
	v_pk_fma_f32 v[170:171], v[186:187], v[170:171], v[202:203]
	v_pk_fma_f32 v[4:5], v[168:169], s[26:27], v[4:5] op_sel_hi:[1,0,1]
	v_pk_fma_f32 v[6:7], v[170:171], s[26:27], v[6:7] op_sel_hi:[1,0,1]
	v_pk_add_f32 v[4:5], v[216:217], v[4:5]
	v_pk_add_f32 v[6:7], v[218:219], v[6:7]
	v_cvt_pk_bf16_f32 v136, v4, v5
	v_cvt_pk_bf16_f32 v137, v6, v7
	v_lshlrev_b32_e32 v168, 16, v136
	v_and_b32_e32 v169, 0xffff0000, v136
	v_lshlrev_b32_e32 v170, 16, v137
	v_and_b32_e32 v171, 0xffff0000, v137
	v_add_f32_e32 v134, v134, v168
	v_fmac_f32_e32 v135, v168, v168
	v_add_f32_e32 v134, v134, v169
	v_fmac_f32_e32 v135, v169, v169
	v_add_f32_e32 v134, v134, v170
	v_fmac_f32_e32 v135, v170, v170
	v_add_f32_e32 v134, v134, v171
	v_fmac_f32_e32 v135, v171, v171
	s_waitcnt vmcnt(15)
	v_lshlrev_b32_e32 v168, 16, v154
	v_and_b32_e32 v169, 0xffff0000, v154
	v_lshlrev_b32_e32 v170, 16, v155
	v_and_b32_e32 v171, 0xffff0000, v155
	v_pk_add_f32 v[168:169], v[168:169], v[162:163] op_sel_hi:[1,0] neg_lo:[0,1] neg_hi:[0,1]
	v_pk_add_f32 v[170:171], v[170:171], v[162:163] op_sel_hi:[1,0] neg_lo:[0,1] neg_hi:[0,1]
	v_pk_mul_f32 v[168:169], v[168:169], v[166:167] op_sel_hi:[1,0]
	v_pk_mul_f32 v[170:171], v[170:171], v[166:167] op_sel_hi:[1,0]
	v_pk_fma_f32 v[168:169], v[188:189], v[168:169], v[204:205]
	v_pk_fma_f32 v[170:171], v[190:191], v[170:171], v[206:207]
	v_pk_fma_f32 v[0:1], v[168:169], s[26:27], v[0:1] op_sel_hi:[1,0,1]
	v_pk_fma_f32 v[2:3], v[170:171], s[26:27], v[2:3] op_sel_hi:[1,0,1]
	v_pk_add_f32 v[0:1], v[220:221], v[0:1]
	v_pk_add_f32 v[2:3], v[222:223], v[2:3]
	v_cvt_pk_bf16_f32 v138, v0, v1
	v_cvt_pk_bf16_f32 v139, v2, v3
	v_lshlrev_b32_e32 v168, 16, v138
	v_and_b32_e32 v169, 0xffff0000, v138
	v_lshlrev_b32_e32 v170, 16, v139
	v_and_b32_e32 v171, 0xffff0000, v139
	v_add_f32_e32 v134, v134, v168
	v_fmac_f32_e32 v135, v168, v168
	v_add_f32_e32 v134, v134, v169
	v_fmac_f32_e32 v135, v169, v169
	v_add_f32_e32 v134, v134, v170
	v_fmac_f32_e32 v135, v170, v170
	v_add_f32_e32 v134, v134, v171
	v_fmac_f32_e32 v135, v171, v171
	v_permlane16_swap_b32_e32 v136, v138
	v_permlane16_swap_b32_e32 v137, v139
	v_add_u32_e32 v133, 0x8000, v132
	global_store_dwordx4 v133, v[136:139], s[14:15]
	v_mov_b32_e32 v140, v134
	v_mov_b32_e32 v141, v135
	s_nop 0
	v_permlane16_swap_b32_e32 v134, v140
	v_permlane16_swap_b32_e32 v135, v141
	v_add_f32_e32 v134, v134, v140
	v_add_f32_e32 v135, v135, v141
	v_mov_b32_e32 v140, v134
	v_mov_b32_e32 v141, v135
	s_nop 0
	v_permlane32_swap_b32_e32 v134, v140
	v_permlane32_swap_b32_e32 v135, v141
	v_add_f32_e32 v134, v134, v140
	v_add_f32_e32 v135, v135, v141
	s_and_saveexec_b64 s[10:11], s[4:5]
	global_atomic_add_f32 v175, v134, s[12:13] offset:1408
	global_atomic_add_f32 v175, v135, s[12:13] offset:1412
	s_or_b64 exec, exec, s[10:11]
	s_mov_b64 s[10:11], exec
	s_branch .LBB0_486

; __global__ __launch_bounds__(512, 2) void mega(Params p) {
	.amdhsa_kernel _Z4mega6Params
		.amdhsa_group_segment_fixed_size 16
		.amdhsa_private_segment_fixed_size 0
		.amdhsa_kernarg_size 456
		.amdhsa_user_sgpr_count 2
		.amdhsa_user_sgpr_dispatch_ptr 0
		.amdhsa_user_sgpr_queue_ptr 0
		.amdhsa_user_sgpr_kernarg_segment_ptr 1
		.amdhsa_user_sgpr_dispatch_id 0
		.amdhsa_user_sgpr_kernarg_preload_length 0
		.amdhsa_user_sgpr_kernarg_preload_offset 0
		.amdhsa_user_sgpr_private_segment_size 0
		.amdhsa_uses_dynamic_stack 0
		.amdhsa_enable_private_segment 0
		.amdhsa_system_sgpr_workgroup_id_x 1
		.amdhsa_system_sgpr_workgroup_id_y 0
		.amdhsa_system_sgpr_workgroup_id_z 0
		.amdhsa_system_sgpr_workgroup_info 0
		.amdhsa_system_vgpr_workitem_id 2
		.amdhsa_next_free_vgpr 256
		.amdhsa_next_free_sgpr 102
		.amdhsa_accum_offset 256
		.amdhsa_reserve_vcc 1
		.amdhsa_float_round_mode_32 0
		.amdhsa_float_round_mode_16_64 0
		.amdhsa_float_denorm_mode_32 3
		.amdhsa_float_denorm_mode_16_64 3
		.amdhsa_dx10_clamp 1
		.amdhsa_ieee_mode 1
		.amdhsa_fp16_overflow 0
		.amdhsa_tg_split 0
		.amdhsa_exception_fp_ieee_invalid_op 0
		.amdhsa_exception_fp_denorm_src 0
		.amdhsa_exception_fp_ieee_div_zero 0
		.amdhsa_exception_fp_ieee_overflow 0
		.amdhsa_exception_fp_ieee_underflow 0
		.amdhsa_exception_fp_ieee_inexact 0
		.amdhsa_exception_int_div_zero 0
	.end_amdhsa_kernel

; __global__ __launch_bounds__(512, 2) void mega(Params p) {
amdhsa.kernels:
  - .agpr_count:     0
    .args:
      - .offset:         0
        .size:           200
        .value_kind:     by_value
      - .offset:         200
        .size:           4
        .value_kind:     hidden_block_count_x
      - .offset:         204
        .size:           4
        .value_kind:     hidden_block_count_y
      - .offset:         208
        .size:           4
        .value_kind:     hidden_block_count_z
      - .offset:         212
        .size:           2
        .value_kind:     hidden_group_size_x
      - .offset:         214
        .size:           2
        .value_kind:     hidden_group_size_y
      - .offset:         216
        .size:           2
        .value_kind:     hidden_group_size_z
      - .offset:         218
        .size:           2
        .value_kind:     hidden_remainder_x
      - .offset:         220
        .size:           2
        .value_kind:     hidden_remainder_y
      - .offset:         222
        .size:           2
        .value_kind:     hidden_remainder_z
      - .offset:         240
        .size:           8
        .value_kind:     hidden_global_offset_x
      - .offset:         248
        .size:           8
        .value_kind:     hidden_global_offset_y
      - .offset:         256
        .size:           8
        .value_kind:     hidden_global_offset_z
      - .offset:         264
        .size:           2
        .value_kind:     hidden_grid_dims
      - .offset:         288
        .size:           8
        .value_kind:     hidden_multigrid_sync_arg
      - .offset:         320
        .size:           4
        .value_kind:     hidden_dynamic_lds_size
    .group_segment_fixed_size: 16
    .kernarg_segment_align: 8
    .kernarg_segment_size: 456
    .language:       OpenCL C
    .language_version:
      - 2
      - 0
    .max_flat_workgroup_size: 512
    .name:           _Z4mega6Params
    .private_segment_fixed_size: 0
    .sgpr_count:     108
    .sgpr_spill_count: 28
    .symbol:         _Z4mega6Params.kd
    .uniform_work_group_size: 1
    .uses_dynamic_stack: false
    .vgpr_count:     256
    .vgpr_spill_count: 0
    .wavefront_size: 64
